# QKV epilogue QK part and EpiResid P (bf16) stores lane-transposed via ds_bpermute (contiguous 64B per 4 lanes)
# speedup vs baseline: 1.0123x; 1.0075x over previous
; __device__ __forceinline__ float ss_rinv(u64 v) { return __builtin_amdgcn_rsqf((float)v * SS_INV + 1e-6f); }
; __device__ __forceinline__ unsigned cvtpk(float lo, float hi) { f32x2 v = {lo, hi}; bf16x2_t b = __builtin_convertvector(v, bf16x2_t); return __builtin_bit_cast(unsigned, b); }
;     __device__ __forceinline__ void operator()(const f32x4 (&acc)[2][2][4][2], const pg8::Unit& u, int wr, int wc, int fr, int fq) const {
;     ...
;         for (int ai = 0; ai < 2; ++ai)
; #pragma unroll
;             for (int m = 0; m < 4; ++m) {
;                 const int lrow = u.pm * 256 + ai * 128 + wr * 64 + m * 16 + fr, grow = row_base + lrow;
;                 if (grow >= MREAL) continue;
;                 const float ri = ss_rinv(rowss[grow]);
; #pragma unroll
;                 for (int bj = 0; bj < 2; ++bj) {
;                     const int col0 = u.pn * 256 + bj * 128 + wc * 32 + 8 * fq;
;                     f32x4 v0 = acc[ai][bj][m][0] * ri, v1 = acc[ai][bj][m][1] * ri;
;                     if (MODE == 1) {
; #pragma unroll
;                         for (int i = 0; i < 4; ++i) { const float a = fmaxf(v0[i], 0.f), b = fmaxf(v1[i], 0.f); v0[i] = a * a; v1[i] = b * b; }
;                         u32x4 w; w.x = cvtpk(v0[0], v0[1]); w.y = cvtpk(v0[2], v0[3]); w.z = cvtpk(v1[0], v1[1]); w.w = cvtpk(v1[2], v1[3]);
;                         *(u32x4*)(O + (size_t)lrow * DFF + col0) = w;
;                     } else {
;                         if (col0 < 1280) {
;                             u32x4 w; w.x = cvtpk(v0[0], v0[1]); w.y = cvtpk(v0[2], v0[3]); w.z = cvtpk(v1[0], v1[1]); w.w = cvtpk(v1[2], v1[3]);
;                             *(u32x4*)(O + (size_t)grow * 1280 + col0) = w;
;                         } else {
;                             int s, p, L; row_decode(grow, s, p, L);
;                             const int LS = seq_LS(s);
;                             bf16_t* dst = VT + seq_off_ch(s) / 4 + (size_t)(col0 - 1280) * LS + XPAD + p;
; #pragma unroll
;                             for (int i = 0; i < 4; ++i) { dst[(size_t)i * LS] = (bf16_t)(cvtpk(v0[i], 0.f) & 0xffffu); dst[(size_t)(4 + i) * LS] = (bf16_t)(cvtpk(v1[i], 0.f) & 0xffffu); }
;                         }
.LBB0_442:
	v_mbcnt_lo_u32_b32 v245, -1, 0
	v_mbcnt_hi_u32_b32 v245, -1, v245
	v_and_b32_e32 v244, 3, v245
	v_lshlrev_b32_e32 v244, 6, v244
	v_and_b32_e32 v246, 60, v245
	v_or_b32_e32 v244, v244, v246
	v_lshrrev_b32_e32 v246, 2, v245
	v_and_b32_e32 v247, 15, v245
	v_sub_u32_e32 v246, v246, v247
	v_mul_i32_i24_e32 v242, 0xa00, v246
	v_and_b32_e32 v246, 3, v245
	v_lshrrev_b32_e32 v247, 4, v245
	v_sub_u32_e32 v246, v246, v247
	v_lshl_add_u32 v242, v246, 4, v242
	v_ashrrev_i32_e32 v243, 31, v242
	v_lshl_add_u32 v144, s6, 8, v163
	v_lshl_or_b32 v142, s2, 8, v165
	v_cmp_gt_i32_e32 vcc, s54, v144
	v_ashrrev_i32_e32 v145, 31, v144
	v_lshl_add_u64 v[188:189], v[144:145], 3, s[16:17]
	global_load_dwordx2 v[172:173], v[188:189], off
	global_load_dwordx2 v[174:175], v[188:189], off offset:128
	global_load_dwordx2 v[176:177], v[188:189], off offset:256
	global_load_dwordx2 v[178:179], v[188:189], off offset:384
	global_load_dwordx2 v[180:181], v[188:189], off offset:1024
	global_load_dwordx2 v[182:183], v[188:189], off offset:1152
	global_load_dwordx2 v[184:185], v[188:189], off offset:1280
	global_load_dwordx2 v[186:187], v[188:189], off offset:1408
	s_waitcnt vmcnt(0)
	v_ashrrev_i32_e32 v167, 13, v144
	s_and_saveexec_b64 s[28:29], vcc
	s_cbranch_execz .LBB0_459
	v_mov_b64_e32 v[146:147], v[172:173]
	s_mov_b32 s6, 0x18000
	s_mov_b32 s2, 0x8000
	v_cmp_gt_i32_e64 s[2:3], s2, v144
	v_ffbh_u32_e32 v32, v147
	v_min_u32_e32 v32, 32, v32
	v_lshlrev_b64 v[146:147], v32, v[146:147]
	v_min_u32_e32 v143, 1, v146
	v_or_b32_e32 v143, v147, v143
	v_cvt_f32_u32_e32 v143, v143
	v_sub_u32_e32 v32, 32, v32
	v_ldexp_f32 v32, v143, v32
	v_fmamk_f32 v32, v32, 0x30800000, v203
	v_rsq_f32_e32 v158, v32
	v_subrev_co_u32_e32 v32, vcc, s6, v144
	v_add_u32_e32 v143, 0xffff8000, v144
	s_movk_i32 s6, 0xfcf
	v_lshrrev_b32_e32 v143, 12, v143
	v_and_or_b32 v168, v144, s6, 16
	s_movk_i32 s6, 0x1fcf
	v_lshrrev_b32_e32 v32, 4, v32
	v_add_u32_e32 v143, 4, v143
	v_and_or_b32 v169, v144, s6, 16
	s_movk_i32 s6, 0x4ff
	v_pk_mul_f32 v[128:129], v[128:129], v[158:159] op_sel_hi:[1,0]
	v_pk_mul_f32 v[126:127], v[126:127], v[158:159] op_sel_hi:[1,0]
	v_pk_mul_f32 v[124:125], v[124:125], v[158:159] op_sel_hi:[1,0]
	v_pk_mul_f32 v[122:123], v[122:123], v[158:159] op_sel_hi:[1,0]
	v_cmp_lt_i32_e64 s[6:7], s6, v142
	v_cndmask_b32_e32 v170, v32, v143, vcc
	s_and_saveexec_b64 s[8:9], s[6:7]
	s_xor_b64 s[30:31], exec, s[8:9]
	s_cbranch_execz .LBB0_449
	v_cndmask_b32_e64 v32, v170, v167, s[2:3]
	v_cmp_gt_i32_e64 s[6:7], 4, v32
	v_cmp_lt_i32_e64 s[8:9], 3, v32
	s_and_saveexec_b64 s[50:51], s[8:9]
	s_xor_b64 s[8:9], exec, s[50:51]
	v_add_u32_e32 v32, -4, v32
	s_mov_b32 s21, 0x410000
	v_mov_b64_e32 v[146:147], 0x2040000
	v_mad_u64_u32 v[160:161], s[50:51], v32, s21, v[146:147]
	s_andn2_saveexec_b64 s[8:9], s[8:9]
	s_mov_b32 s21, 0x810000
	v_mad_i64_i32 v[160:161], s[50:51], v32, s21, 0
	s_or_b64 exec, exec, s[8:9]
	v_mov_b32_e32 v143, 0x1040
	v_mov_b32_e32 v146, 0x2040
	v_cndmask_b32_e64 v143, v143, v146, s[6:7]
	v_lshrrev_b64 v[146:147], 1, v[160:161]
	v_cndmask_b32_e32 v32, v162, v168, vcc
	v_and_b32_e32 v146, -2, v146
	v_add_u32_e32 v148, 0xfffffb00, v142
	v_cndmask_b32_e64 v32, v32, v169, s[2:3]
	v_lshl_add_u64 v[146:147], s[14:15], 0, v[146:147]
	v_mad_u64_u32 v[148:149], s[6:7], v143, v148, 0
	v_lshl_add_u64 v[146:147], v[148:149], 1, v[146:147]
	v_lshlrev_b32_e32 v32, 1, v32
	v_lshl_add_u64 v[146:147], v[146:147], 0, v[32:33]
	v_lshlrev_b32_e32 v148, 3, v143
	v_mov_b32_e32 v149, v33
	v_cvt_pk_bf16_f32 v122, v122, s0
	v_lshl_add_u64 v[148:149], v[146:147], 0, v[148:149]
	v_cvt_pk_bf16_f32 v32, v126, s0
	global_store_short v[148:149], v122, off offset:96
	v_cvt_pk_bf16_f32 v122, v127, s0
	v_lshlrev_b32_e32 v126, 1, v143
	v_mov_b32_e32 v127, v33
	v_lshl_add_u64 v[126:127], v[146:147], 0, v[126:127]
	global_store_short v[126:127], v122, off offset:96
	v_mul_u32_u24_e32 v122, 5, v143
	v_cvt_pk_bf16_f32 v126, v123, s0
	v_lshlrev_b32_e32 v122, 1, v122
	v_mov_b32_e32 v123, v33
	global_store_short v[146:147], v32, off offset:96
	v_lshlrev_b32_e32 v32, 2, v143
	v_lshl_add_u64 v[122:123], v[146:147], 0, v[122:123]
	global_store_short v[122:123], v126, off offset:96
	v_lshl_add_u64 v[122:123], v[146:147], 0, v[32:33]
	v_mul_u32_u24_e32 v32, 6, v143
	v_cvt_pk_bf16_f32 v126, v128, s0
	v_lshlrev_b32_e32 v32, 1, v32
	global_store_short v[122:123], v126, off offset:96
	v_lshl_add_u64 v[122:123], v[146:147], 0, v[32:33]
	v_mul_u32_u24_e32 v32, 3, v143
	v_cvt_pk_bf16_f32 v124, v124, s0
	v_lshlrev_b32_e32 v32, 1, v32
	global_store_short v[122:123], v124, off offset:96
	v_lshl_add_u64 v[122:123], v[146:147], 0, v[32:33]
	v_mul_u32_u24_e32 v32, 7, v143
	v_cvt_pk_bf16_f32 v124, v129, s0
	v_lshlrev_b32_e32 v32, 1, v32
	global_store_short v[122:123], v124, off offset:96
	v_cvt_pk_bf16_f32 v124, v125, s0
	v_lshl_add_u64 v[122:123], v[146:147], 0, v[32:33]
	global_store_short v[122:123], v124, off offset:96
.LBB0_449:
	s_or_saveexec_b64 s[6:7], s[30:31]
	s_movk_i32 s8, 0xa00
	v_mad_i64_i32 v[146:147], s[8:9], v144, s8, 0
	v_lshl_add_u64 v[160:161], s[12:13], 0, v[146:147]
	s_xor_b64 exec, exec, s[6:7]
	s_cbranch_execz .LBB0_451
	v_ashrrev_i32_e32 v143, 31, v142
	v_cvt_pk_bf16_f32 v126, v126, v127
	v_cvt_pk_bf16_f32 v127, v128, v129
	v_cvt_pk_bf16_f32 v128, v122, v123
	v_cvt_pk_bf16_f32 v129, v124, v125
	v_lshl_add_u64 v[122:123], v[142:143], 1, v[160:161]
	ds_bpermute_b32 v126, v244, v126
	ds_bpermute_b32 v127, v244, v127
	ds_bpermute_b32 v128, v244, v128
	ds_bpermute_b32 v129, v244, v129
	v_lshl_add_u64 v[246:247], v[242:243], 0, v[122:123]
	s_waitcnt lgkmcnt(0)
	global_store_dwordx4 v[246:247], v[126:129], off

; __device__ __forceinline__ unsigned cvtpk(float lo, float hi) { f32x2 v = {lo, hi}; bf16x2_t b = __builtin_convertvector(v, bf16x2_t); return __builtin_bit_cast(unsigned, b); }
;     __device__ __forceinline__ void operator()(const f32x4 (&acc)[2][2][4][2], const pg8::Unit& u, int wr, int wc, int fr, int fq) const {
;     ...
;                         if (col0 < 1280) {
;                             u32x4 w; w.x = cvtpk(v0[0], v0[1]); w.y = cvtpk(v0[2], v0[3]); w.z = cvtpk(v1[0], v1[1]); w.w = cvtpk(v1[2], v1[3]);
;                             *(u32x4*)(O + (size_t)grow * 1280 + col0) = w;
.LBB0_457:
	s_andn2_saveexec_b64 s[2:3], s[30:31]
	s_cbranch_execz .LBB0_459
	v_ashrrev_i32_e32 v143, 31, v142
	v_cvt_pk_bf16_f32 v118, v118, v119
	v_cvt_pk_bf16_f32 v119, v120, v121
	v_cvt_pk_bf16_f32 v120, v114, v115
	v_cvt_pk_bf16_f32 v121, v116, v117
	v_lshl_add_u64 v[114:115], v[142:143], 1, v[160:161]
	ds_bpermute_b32 v118, v244, v118
	ds_bpermute_b32 v119, v244, v119
	ds_bpermute_b32 v120, v244, v120
	ds_bpermute_b32 v121, v244, v121
	v_lshl_add_u64 v[246:247], v[242:243], 0, v[114:115]
	s_waitcnt lgkmcnt(0)
	global_store_dwordx4 v[246:247], v[118:121], off offset:256

; __device__ __forceinline__ unsigned cvtpk(float lo, float hi) { f32x2 v = {lo, hi}; bf16x2_t b = __builtin_convertvector(v, bf16x2_t); return __builtin_bit_cast(unsigned, b); }
;     __device__ __forceinline__ void operator()(const f32x4 (&acc)[2][2][4][2], const pg8::Unit& u, int wr, int wc, int fr, int fq) const {
;     ...
;                         if (col0 < 1280) {
;                             u32x4 w; w.x = cvtpk(v0[0], v0[1]); w.y = cvtpk(v0[2], v0[3]); w.z = cvtpk(v1[0], v1[1]); w.w = cvtpk(v1[2], v1[3]);
;                             *(u32x4*)(O + (size_t)grow * 1280 + col0) = w;
.LBB0_466:
	s_or_saveexec_b64 s[6:7], s[30:31]
	s_movk_i32 s8, 0xa00
	v_mad_i64_i32 v[116:117], s[8:9], v115, s8, 0
	v_lshl_add_u64 v[116:117], s[12:13], 0, v[116:117]
	s_xor_b64 exec, exec, s[6:7]
	s_cbranch_execz .LBB0_468
	v_ashrrev_i32_e32 v143, 31, v142
	v_cvt_pk_bf16_f32 v110, v110, v111
	v_cvt_pk_bf16_f32 v111, v112, v113
	v_cvt_pk_bf16_f32 v112, v106, v107
	v_cvt_pk_bf16_f32 v113, v108, v109
	v_lshl_add_u64 v[106:107], v[142:143], 1, v[116:117]
	ds_bpermute_b32 v110, v244, v110
	ds_bpermute_b32 v111, v244, v111
	ds_bpermute_b32 v112, v244, v112
	ds_bpermute_b32 v113, v244, v113
	v_lshl_add_u64 v[246:247], v[242:243], 0, v[106:107]
	s_waitcnt lgkmcnt(0)
	global_store_dwordx4 v[246:247], v[110:113], off

; __device__ __forceinline__ unsigned cvtpk(float lo, float hi) { f32x2 v = {lo, hi}; bf16x2_t b = __builtin_convertvector(v, bf16x2_t); return __builtin_bit_cast(unsigned, b); }
;     __device__ __forceinline__ void operator()(const f32x4 (&acc)[2][2][4][2], const pg8::Unit& u, int wr, int wc, int fr, int fq) const {
;     ...
;                         if (col0 < 1280) {
;                             u32x4 w; w.x = cvtpk(v0[0], v0[1]); w.y = cvtpk(v0[2], v0[3]); w.z = cvtpk(v1[0], v1[1]); w.w = cvtpk(v1[2], v1[3]);
;                             *(u32x4*)(O + (size_t)grow * 1280 + col0) = w;
.LBB0_474:
	s_andn2_saveexec_b64 s[2:3], s[30:31]
	s_cbranch_execz .LBB0_476
	v_ashrrev_i32_e32 v143, 31, v142
	v_cvt_pk_bf16_f32 v102, v102, v103
	v_cvt_pk_bf16_f32 v103, v104, v105
	v_cvt_pk_bf16_f32 v104, v98, v99
	v_cvt_pk_bf16_f32 v105, v100, v101
	v_lshl_add_u64 v[98:99], v[142:143], 1, v[116:117]
	ds_bpermute_b32 v102, v244, v102
	ds_bpermute_b32 v103, v244, v103
	ds_bpermute_b32 v104, v244, v104
	ds_bpermute_b32 v105, v244, v105
	v_lshl_add_u64 v[246:247], v[242:243], 0, v[98:99]
	s_waitcnt lgkmcnt(0)
	global_store_dwordx4 v[246:247], v[102:105], off offset:256

; __device__ __forceinline__ unsigned cvtpk(float lo, float hi) { f32x2 v = {lo, hi}; bf16x2_t b = __builtin_convertvector(v, bf16x2_t); return __builtin_bit_cast(unsigned, b); }
;     __device__ __forceinline__ void operator()(const f32x4 (&acc)[2][2][4][2], const pg8::Unit& u, int wr, int wc, int fr, int fq) const {
;     ...
;                         if (col0 < 1280) {
;                             u32x4 w; w.x = cvtpk(v0[0], v0[1]); w.y = cvtpk(v0[2], v0[3]); w.z = cvtpk(v1[0], v1[1]); w.w = cvtpk(v1[2], v1[3]);
;                             *(u32x4*)(O + (size_t)grow * 1280 + col0) = w;
.LBB0_483:
	s_or_saveexec_b64 s[6:7], s[30:31]
	s_movk_i32 s8, 0xa00
	v_mad_i64_i32 v[100:101], s[8:9], v99, s8, 0
	v_lshl_add_u64 v[100:101], s[12:13], 0, v[100:101]
	s_xor_b64 exec, exec, s[6:7]
	s_cbranch_execz .LBB0_485
	v_ashrrev_i32_e32 v143, 31, v142
	v_cvt_pk_bf16_f32 v94, v94, v95
	v_cvt_pk_bf16_f32 v95, v96, v97
	v_cvt_pk_bf16_f32 v96, v90, v91
	v_cvt_pk_bf16_f32 v97, v92, v93
	v_lshl_add_u64 v[90:91], v[142:143], 1, v[100:101]
	ds_bpermute_b32 v94, v244, v94
	ds_bpermute_b32 v95, v244, v95
	ds_bpermute_b32 v96, v244, v96
	ds_bpermute_b32 v97, v244, v97
	v_lshl_add_u64 v[246:247], v[242:243], 0, v[90:91]
	s_waitcnt lgkmcnt(0)
	global_store_dwordx4 v[246:247], v[94:97], off

; __device__ __forceinline__ unsigned cvtpk(float lo, float hi) { f32x2 v = {lo, hi}; bf16x2_t b = __builtin_convertvector(v, bf16x2_t); return __builtin_bit_cast(unsigned, b); }
;     __device__ __forceinline__ void operator()(const f32x4 (&acc)[2][2][4][2], const pg8::Unit& u, int wr, int wc, int fr, int fq) const {
;     ...
;                         if (col0 < 1280) {
;                             u32x4 w; w.x = cvtpk(v0[0], v0[1]); w.y = cvtpk(v0[2], v0[3]); w.z = cvtpk(v1[0], v1[1]); w.w = cvtpk(v1[2], v1[3]);
;                             *(u32x4*)(O + (size_t)grow * 1280 + col0) = w;
.LBB0_491:
	s_andn2_saveexec_b64 s[2:3], s[30:31]
	s_cbranch_execz .LBB0_493
	v_ashrrev_i32_e32 v143, 31, v142
	v_cvt_pk_bf16_f32 v86, v86, v87
	v_cvt_pk_bf16_f32 v87, v88, v89
	v_cvt_pk_bf16_f32 v88, v82, v83
	v_cvt_pk_bf16_f32 v89, v84, v85
	v_lshl_add_u64 v[82:83], v[142:143], 1, v[100:101]
	ds_bpermute_b32 v86, v244, v86
	ds_bpermute_b32 v87, v244, v87
	ds_bpermute_b32 v88, v244, v88
	ds_bpermute_b32 v89, v244, v89
	v_lshl_add_u64 v[246:247], v[242:243], 0, v[82:83]
	s_waitcnt lgkmcnt(0)
	global_store_dwordx4 v[246:247], v[86:89], off offset:256

; __device__ __forceinline__ unsigned cvtpk(float lo, float hi) { f32x2 v = {lo, hi}; bf16x2_t b = __builtin_convertvector(v, bf16x2_t); return __builtin_bit_cast(unsigned, b); }
;     __device__ __forceinline__ void operator()(const f32x4 (&acc)[2][2][4][2], const pg8::Unit& u, int wr, int wc, int fr, int fq) const {
;     ...
;                         if (col0 < 1280) {
;                             u32x4 w; w.x = cvtpk(v0[0], v0[1]); w.y = cvtpk(v0[2], v0[3]); w.z = cvtpk(v1[0], v1[1]); w.w = cvtpk(v1[2], v1[3]);
;                             *(u32x4*)(O + (size_t)grow * 1280 + col0) = w;
.LBB0_500:
	s_or_saveexec_b64 s[6:7], s[30:31]
	s_movk_i32 s8, 0xa00
	v_mad_i64_i32 v[84:85], s[8:9], v83, s8, 0
	v_lshl_add_u64 v[84:85], s[12:13], 0, v[84:85]
	s_xor_b64 exec, exec, s[6:7]
	s_cbranch_execz .LBB0_502
	v_ashrrev_i32_e32 v143, 31, v142
	v_cvt_pk_bf16_f32 v78, v78, v79
	v_cvt_pk_bf16_f32 v79, v80, v81
	v_cvt_pk_bf16_f32 v80, v74, v75
	v_cvt_pk_bf16_f32 v81, v76, v77
	v_lshl_add_u64 v[74:75], v[142:143], 1, v[84:85]
	ds_bpermute_b32 v78, v244, v78
	ds_bpermute_b32 v79, v244, v79
	ds_bpermute_b32 v80, v244, v80
	ds_bpermute_b32 v81, v244, v81
	v_lshl_add_u64 v[246:247], v[242:243], 0, v[74:75]
	s_waitcnt lgkmcnt(0)
	global_store_dwordx4 v[246:247], v[78:81], off

; __device__ __forceinline__ unsigned cvtpk(float lo, float hi) { f32x2 v = {lo, hi}; bf16x2_t b = __builtin_convertvector(v, bf16x2_t); return __builtin_bit_cast(unsigned, b); }
;     __device__ __forceinline__ void operator()(const f32x4 (&acc)[2][2][4][2], const pg8::Unit& u, int wr, int wc, int fr, int fq) const {
;     ...
;                         if (col0 < 1280) {
;                             u32x4 w; w.x = cvtpk(v0[0], v0[1]); w.y = cvtpk(v0[2], v0[3]); w.z = cvtpk(v1[0], v1[1]); w.w = cvtpk(v1[2], v1[3]);
;                             *(u32x4*)(O + (size_t)grow * 1280 + col0) = w;
.LBB0_508:
	s_andn2_saveexec_b64 s[2:3], s[30:31]
	s_cbranch_execz .LBB0_510
	v_ashrrev_i32_e32 v143, 31, v142
	v_cvt_pk_bf16_f32 v70, v70, v71
	v_cvt_pk_bf16_f32 v71, v72, v73
	v_cvt_pk_bf16_f32 v72, v66, v67
	v_cvt_pk_bf16_f32 v73, v68, v69
	v_lshl_add_u64 v[66:67], v[142:143], 1, v[84:85]
	ds_bpermute_b32 v70, v244, v70
	ds_bpermute_b32 v71, v244, v71
	ds_bpermute_b32 v72, v244, v72
	ds_bpermute_b32 v73, v244, v73
	v_lshl_add_u64 v[246:247], v[242:243], 0, v[66:67]
	s_waitcnt lgkmcnt(0)
	global_store_dwordx4 v[246:247], v[70:73], off offset:256

; __device__ __forceinline__ unsigned cvtpk(float lo, float hi) { f32x2 v = {lo, hi}; bf16x2_t b = __builtin_convertvector(v, bf16x2_t); return __builtin_bit_cast(unsigned, b); }
;     __device__ __forceinline__ void operator()(const f32x4 (&acc)[2][2][4][2], const pg8::Unit& u, int wr, int wc, int fr, int fq) const {
;     ...
;                         if (col0 < 1280) {
;                             u32x4 w; w.x = cvtpk(v0[0], v0[1]); w.y = cvtpk(v0[2], v0[3]); w.z = cvtpk(v1[0], v1[1]); w.w = cvtpk(v1[2], v1[3]);
;                             *(u32x4*)(O + (size_t)grow * 1280 + col0) = w;
.LBB0_517:
	s_or_saveexec_b64 s[6:7], s[30:31]
	s_movk_i32 s8, 0xa00
	v_mad_i64_i32 v[68:69], s[8:9], v67, s8, 0
	v_lshl_add_u64 v[68:69], s[12:13], 0, v[68:69]
	s_xor_b64 exec, exec, s[6:7]
	s_cbranch_execz .LBB0_519
	v_ashrrev_i32_e32 v143, 31, v142
	v_cvt_pk_bf16_f32 v62, v62, v63
	v_cvt_pk_bf16_f32 v63, v64, v65
	v_cvt_pk_bf16_f32 v64, v58, v59
	v_cvt_pk_bf16_f32 v65, v60, v61
	v_lshl_add_u64 v[58:59], v[142:143], 1, v[68:69]
	ds_bpermute_b32 v62, v244, v62
	ds_bpermute_b32 v63, v244, v63
	ds_bpermute_b32 v64, v244, v64
	ds_bpermute_b32 v65, v244, v65
	v_lshl_add_u64 v[246:247], v[242:243], 0, v[58:59]
	s_waitcnt lgkmcnt(0)
	global_store_dwordx4 v[246:247], v[62:65], off

; __device__ __forceinline__ unsigned cvtpk(float lo, float hi) { f32x2 v = {lo, hi}; bf16x2_t b = __builtin_convertvector(v, bf16x2_t); return __builtin_bit_cast(unsigned, b); }
;     __device__ __forceinline__ void operator()(const f32x4 (&acc)[2][2][4][2], const pg8::Unit& u, int wr, int wc, int fr, int fq) const {
;     ...
;                         if (col0 < 1280) {
;                             u32x4 w; w.x = cvtpk(v0[0], v0[1]); w.y = cvtpk(v0[2], v0[3]); w.z = cvtpk(v1[0], v1[1]); w.w = cvtpk(v1[2], v1[3]);
;                             *(u32x4*)(O + (size_t)grow * 1280 + col0) = w;
.LBB0_525:
	s_andn2_saveexec_b64 s[2:3], s[30:31]
	s_cbranch_execz .LBB0_527
	v_ashrrev_i32_e32 v143, 31, v142
	v_cvt_pk_bf16_f32 v54, v54, v55
	v_cvt_pk_bf16_f32 v55, v56, v57
	v_cvt_pk_bf16_f32 v56, v50, v51
	v_cvt_pk_bf16_f32 v57, v52, v53
	v_lshl_add_u64 v[50:51], v[142:143], 1, v[68:69]
	ds_bpermute_b32 v54, v244, v54
	ds_bpermute_b32 v55, v244, v55
	ds_bpermute_b32 v56, v244, v56
	ds_bpermute_b32 v57, v244, v57
	v_lshl_add_u64 v[246:247], v[242:243], 0, v[50:51]
	s_waitcnt lgkmcnt(0)
	global_store_dwordx4 v[246:247], v[54:57], off offset:256

; __device__ __forceinline__ unsigned cvtpk(float lo, float hi) { f32x2 v = {lo, hi}; bf16x2_t b = __builtin_convertvector(v, bf16x2_t); return __builtin_bit_cast(unsigned, b); }
;     __device__ __forceinline__ void operator()(const f32x4 (&acc)[2][2][4][2], const pg8::Unit& u, int wr, int wc, int fr, int fq) const {
;     ...
;                         if (col0 < 1280) {
;                             u32x4 w; w.x = cvtpk(v0[0], v0[1]); w.y = cvtpk(v0[2], v0[3]); w.z = cvtpk(v1[0], v1[1]); w.w = cvtpk(v1[2], v1[3]);
;                             *(u32x4*)(O + (size_t)grow * 1280 + col0) = w;
.LBB0_534:
	s_or_saveexec_b64 s[6:7], s[30:31]
	s_movk_i32 s8, 0xa00
	v_mad_i64_i32 v[52:53], s[8:9], v51, s8, 0
	v_lshl_add_u64 v[52:53], s[12:13], 0, v[52:53]
	s_xor_b64 exec, exec, s[6:7]
	s_cbranch_execz .LBB0_536
	v_ashrrev_i32_e32 v143, 31, v142
	v_cvt_pk_bf16_f32 v46, v46, v47
	v_cvt_pk_bf16_f32 v47, v48, v49
	v_cvt_pk_bf16_f32 v48, v42, v43
	v_cvt_pk_bf16_f32 v49, v44, v45
	v_lshl_add_u64 v[42:43], v[142:143], 1, v[52:53]
	ds_bpermute_b32 v46, v244, v46
	ds_bpermute_b32 v47, v244, v47
	ds_bpermute_b32 v48, v244, v48
	ds_bpermute_b32 v49, v244, v49
	v_lshl_add_u64 v[246:247], v[242:243], 0, v[42:43]
	s_waitcnt lgkmcnt(0)
	global_store_dwordx4 v[246:247], v[46:49], off

; __device__ __forceinline__ unsigned cvtpk(float lo, float hi) { f32x2 v = {lo, hi}; bf16x2_t b = __builtin_convertvector(v, bf16x2_t); return __builtin_bit_cast(unsigned, b); }
;     __device__ __forceinline__ void operator()(const f32x4 (&acc)[2][2][4][2], const pg8::Unit& u, int wr, int wc, int fr, int fq) const {
;     ...
;                         if (col0 < 1280) {
;                             u32x4 w; w.x = cvtpk(v0[0], v0[1]); w.y = cvtpk(v0[2], v0[3]); w.z = cvtpk(v1[0], v1[1]); w.w = cvtpk(v1[2], v1[3]);
;                             *(u32x4*)(O + (size_t)grow * 1280 + col0) = w;
.LBB0_542:
	s_andn2_saveexec_b64 s[2:3], s[30:31]
	s_cbranch_execz .LBB0_544
	v_ashrrev_i32_e32 v143, 31, v142
	v_cvt_pk_bf16_f32 v38, v38, v39
	v_cvt_pk_bf16_f32 v39, v40, v41
	v_cvt_pk_bf16_f32 v40, v34, v35
	v_cvt_pk_bf16_f32 v41, v36, v37
	v_lshl_add_u64 v[34:35], v[142:143], 1, v[52:53]
	ds_bpermute_b32 v38, v244, v38
	ds_bpermute_b32 v39, v244, v39
	ds_bpermute_b32 v40, v244, v40
	ds_bpermute_b32 v41, v244, v41
	v_lshl_add_u64 v[246:247], v[242:243], 0, v[34:35]
	s_waitcnt lgkmcnt(0)
	global_store_dwordx4 v[246:247], v[38:41], off offset:256

; __device__ __forceinline__ unsigned cvtpk(float lo, float hi) { f32x2 v = {lo, hi}; bf16x2_t b = __builtin_convertvector(v, bf16x2_t); return __builtin_bit_cast(unsigned, b); }
;     __device__ __forceinline__ void operator()(const f32x4 (&acc)[2][2][4][2], const pg8::Unit& u, int wr, int wc, int fr, int fq) const {
;     ...
;                         if (col0 < 1280) {
;                             u32x4 w; w.x = cvtpk(v0[0], v0[1]); w.y = cvtpk(v0[2], v0[3]); w.z = cvtpk(v1[0], v1[1]); w.w = cvtpk(v1[2], v1[3]);
;                             *(u32x4*)(O + (size_t)grow * 1280 + col0) = w;
.LBB0_551:
	s_or_saveexec_b64 s[6:7], s[30:31]
	s_movk_i32 s8, 0xa00
	v_mad_i64_i32 v[36:37], s[8:9], v35, s8, 0
	v_lshl_add_u64 v[36:37], s[12:13], 0, v[36:37]
	s_xor_b64 exec, exec, s[6:7]
	s_cbranch_execz .LBB0_553
	v_ashrrev_i32_e32 v143, 31, v142
	v_cvt_pk_bf16_f32 v28, v28, v29
	v_cvt_pk_bf16_f32 v29, v30, v31
	v_cvt_pk_bf16_f32 v30, v24, v25
	v_cvt_pk_bf16_f32 v31, v26, v27
	v_lshl_add_u64 v[24:25], v[142:143], 1, v[36:37]
	ds_bpermute_b32 v28, v244, v28
	ds_bpermute_b32 v29, v244, v29
	ds_bpermute_b32 v30, v244, v30
	ds_bpermute_b32 v31, v244, v31
	v_lshl_add_u64 v[246:247], v[242:243], 0, v[24:25]
	s_waitcnt lgkmcnt(0)
	global_store_dwordx4 v[246:247], v[28:31], off

; __device__ __forceinline__ unsigned cvtpk(float lo, float hi) { f32x2 v = {lo, hi}; bf16x2_t b = __builtin_convertvector(v, bf16x2_t); return __builtin_bit_cast(unsigned, b); }
;     __device__ __forceinline__ void operator()(const f32x4 (&acc)[2][2][4][2], const pg8::Unit& u, int wr, int wc, int fr, int fq) const {
;     ...
;                         if (col0 < 1280) {
;                             u32x4 w; w.x = cvtpk(v0[0], v0[1]); w.y = cvtpk(v0[2], v0[3]); w.z = cvtpk(v1[0], v1[1]); w.w = cvtpk(v1[2], v1[3]);
;                             *(u32x4*)(O + (size_t)grow * 1280 + col0) = w;
.LBB0_559:
	s_andn2_saveexec_b64 s[2:3], s[30:31]
	s_cbranch_execz .LBB0_561
	v_ashrrev_i32_e32 v143, 31, v142
	v_cvt_pk_bf16_f32 v20, v20, v21
	v_cvt_pk_bf16_f32 v21, v22, v23
	v_cvt_pk_bf16_f32 v22, v16, v17
	v_cvt_pk_bf16_f32 v23, v18, v19
	v_lshl_add_u64 v[16:17], v[142:143], 1, v[36:37]
	ds_bpermute_b32 v20, v244, v20
	ds_bpermute_b32 v21, v244, v21
	ds_bpermute_b32 v22, v244, v22
	ds_bpermute_b32 v23, v244, v23
	v_lshl_add_u64 v[246:247], v[242:243], 0, v[16:17]
	s_waitcnt lgkmcnt(0)
	global_store_dwordx4 v[246:247], v[20:23], off offset:256

; __device__ __forceinline__ unsigned cvtpk(float lo, float hi) { f32x2 v = {lo, hi}; bf16x2_t b = __builtin_convertvector(v, bf16x2_t); return __builtin_bit_cast(unsigned, b); }
;     __device__ __forceinline__ void operator()(const f32x4 (&acc)[2][2][4][2], const pg8::Unit& u, int wr, int wc, int fr, int fq) const {
;     ...
;                         if (col0 < 1280) {
;                             u32x4 w; w.x = cvtpk(v0[0], v0[1]); w.y = cvtpk(v0[2], v0[3]); w.z = cvtpk(v1[0], v1[1]); w.w = cvtpk(v1[2], v1[3]);
;                             *(u32x4*)(O + (size_t)grow * 1280 + col0) = w;
.LBB0_568:
	s_or_saveexec_b64 s[6:7], s[30:31]
	s_movk_i32 s8, 0xa00
	v_mad_i64_i32 v[18:19], s[8:9], v17, s8, 0
	v_lshl_add_u64 v[18:19], s[12:13], 0, v[18:19]
	v_ashrrev_i32_e32 v143, 31, v142
	s_xor_b64 exec, exec, s[6:7]
	s_cbranch_execz .LBB0_570
	v_cvt_pk_bf16_f32 v12, v12, v13
	v_cvt_pk_bf16_f32 v13, v14, v15
	v_cvt_pk_bf16_f32 v14, v8, v9
	v_cvt_pk_bf16_f32 v15, v10, v11
	v_lshl_add_u64 v[8:9], v[142:143], 1, v[18:19]
	ds_bpermute_b32 v12, v244, v12
	ds_bpermute_b32 v13, v244, v13
	ds_bpermute_b32 v14, v244, v14
	ds_bpermute_b32 v15, v244, v15
	v_lshl_add_u64 v[246:247], v[242:243], 0, v[8:9]
	s_waitcnt lgkmcnt(0)
	global_store_dwordx4 v[246:247], v[12:15], off

; __device__ __forceinline__ unsigned cvtpk(float lo, float hi) { f32x2 v = {lo, hi}; bf16x2_t b = __builtin_convertvector(v, bf16x2_t); return __builtin_bit_cast(unsigned, b); }
;     __device__ __forceinline__ void operator()(const f32x4 (&acc)[2][2][4][2], const pg8::Unit& u, int wr, int wc, int fr, int fq) const {
;     ...
;                         if (col0 < 1280) {
;                             u32x4 w; w.x = cvtpk(v0[0], v0[1]); w.y = cvtpk(v0[2], v0[3]); w.z = cvtpk(v1[0], v1[1]); w.w = cvtpk(v1[2], v1[3]);
;                             *(u32x4*)(O + (size_t)grow * 1280 + col0) = w;
.LBB0_576:
	s_andn2_saveexec_b64 s[2:3], s[30:31]
	s_cbranch_execz .LBB0_578
	v_cvt_pk_bf16_f32 v4, v4, v5
	v_cvt_pk_bf16_f32 v5, v6, v7
	v_cvt_pk_bf16_f32 v6, v0, v1
	v_cvt_pk_bf16_f32 v7, v2, v3
	v_lshl_add_u64 v[0:1], v[142:143], 1, v[18:19]
	ds_bpermute_b32 v4, v244, v4
	ds_bpermute_b32 v5, v244, v5
	ds_bpermute_b32 v6, v244, v6
	ds_bpermute_b32 v7, v244, v7
	v_lshl_add_u64 v[246:247], v[242:243], 0, v[0:1]
	s_waitcnt lgkmcnt(0)
	global_store_dwordx4 v[246:247], v[4:7], off offset:256

; __device__ __forceinline__ unsigned cvtpk(float lo, float hi) { f32x2 v = {lo, hi}; bf16x2_t b = __builtin_convertvector(v, bf16x2_t); return __builtin_bit_cast(unsigned, b); }
;     __device__ __forceinline__ void operator()(const f32x4 (&acc)[2][2][4][2], const pg8::Unit& u, int wr, int wc, int fr, int fq) const {
;     ...
;                 const int grow = row_base + u.pm * 256 + ai * 128 + wr * 64 + m * 16 + fr;
;                 const bool ok = grow < MREAL;
;                 float ss = 0.f;
;                 if (ok) {
;                     const float* src; float* dst;
;                     if (grow < ROWS_P) { src = srcA + (size_t)grow * DM; dst = dstMain + (size_t)grow * DM; }
;                     else if (grow < ROWS_MAIN) { src = srcB + (size_t)(grow - ROWS_P) * DM; dst = dstMain + (size_t)grow * DM; }
;                     else { const int mr = grow - ROWS_MAIN; src = srcM + (size_t)(mr & meta_mask) * DM; dst = dstM + (size_t)mr * DM; }
; #pragma unroll
;                     for (int bj = 0; bj < 2; ++bj) {
;                         const int col0 = u.pn * 256 + bj * 128 + wc * 32 + 8 * fq;
;                         const f32x4 h0 = *(const f32x4*)(src + col0) + acc[ai][bj][m][0];
;                         const f32x4 h1 = *(const f32x4*)(src + col0 + 4) + acc[ai][bj][m][1];
;                         *(f32x4*)(dst + col0) = h0; *(f32x4*)(dst + col0 + 4) = h1;
;                         if (P) { u32x4 w; w.x = cvtpk(h0[0], h0[1]); w.y = cvtpk(h0[2], h0[3]); w.z = cvtpk(h1[0], h1[1]); w.w = cvtpk(h1[2], h1[3]);
;                             *(u32x4*)(P + (size_t)grow * DM + col0) = w; }
;                         ss += (h0[0] * h0[0] + h0[1] * h0[1]) + (h0[2] * h0[2] + h0[3] * h0[3]) + (h1[0] * h1[0] + h1[1] * h1[1]) + (h1[2] * h1[2] + h1[3] * h1[3]);
;                     }
.LBB0_798:
	s_lshl_b32 vcc_lo, s42, 8
	s_cmp_lt_u32 vcc_lo, 0x18000
	s_cbranch_scc0 .Lepi_old_ao
	s_cmp_lg_u64 s[28:29], 0
	s_cbranch_scc0 .Lepi_old_ao
	s_cmp_lg_u64 s[30:31], 0
	s_cbranch_scc0 .Lepi_old_ao
	s_lshl_b32 vcc_hi, s8, 10
	s_lshl_b32 s8, vcc_lo, 3
	s_add_u32 s8, s16, s8
	s_addc_u32 s9, s17, 0
	s_lshl_b32 s6, vcc_lo, 12
	s_add_u32 vcc_hi, vcc_hi, s6
	s_add_u32 s44, s12, vcc_hi
	s_addc_u32 s45, s13, 0
	s_lshr_b32 s6, vcc_hi, 1
	s_add_u32 s6, s10, s6
	s_addc_u32 s7, s11, 0
	s_cmp_lt_u32 vcc_lo, 0x8000
	s_cselect_b32 s42, s24, s22
	s_cselect_b32 s43, s25, s23
	s_cselect_b32 vcc_lo, 0, 0x8000000
	s_sub_u32 vcc_hi, vcc_hi, vcc_lo
	s_add_u32 s42, s42, vcc_hi
	s_addc_u32 s43, s43, 0
	v_lshlrev_b32_e32 v150, 12, v164
	v_lshl_add_u32 v150, v166, 2, v150
	v_lshrrev_b32_e32 v151, 1, v150
	v_lshlrev_b32_e32 v162, 3, v164
	v_mbcnt_lo_u32_b32 v235, -1, 0
	v_mbcnt_hi_u32_b32 v235, -1, v235
	v_and_b32_e32 v232, 3, v235
	v_lshlrev_b32_e32 v232, 6, v232
	v_and_b32_e32 v236, 60, v235
	v_or_b32_e32 v232, v232, v236
	v_lshrrev_b32_e32 v236, 2, v235
	v_and_b32_e32 v237, 15, v235
	v_sub_u32_e32 v236, v236, v237
	v_lshl_add_u32 v233, v236, 12, v150
	v_and_b32_e32 v236, 3, v235
	v_lshrrev_b32_e32 v237, 4, v235
	v_sub_u32_e32 v236, v236, v237
	v_lshl_add_u32 v233, v236, 5, v233
	v_lshrrev_b32_e32 v234, 1, v233
	global_load_dwordx4 v[168:171], v150, s[42:43]
	global_load_dwordx4 v[172:175], v150, s[42:43] offset:16
	global_load_dwordx4 v[176:179], v150, s[42:43] offset:512
	global_load_dwordx4 v[180:183], v150, s[42:43] offset:528
	s_add_u32 s42, s42, 0x10000
	s_addc_u32 s43, s43, 0
	global_load_dwordx4 v[184:187], v150, s[42:43]
	global_load_dwordx4 v[188:191], v150, s[42:43] offset:16
	global_load_dwordx4 v[192:195], v150, s[42:43] offset:512
	global_load_dwordx4 v[196:199], v150, s[42:43] offset:528
	s_add_u32 s42, s42, 0x10000
	s_addc_u32 s43, s43, 0
	global_load_dwordx4 v[216:219], v150, s[42:43]
	global_load_dwordx4 v[220:223], v150, s[42:43] offset:16
	global_load_dwordx4 v[224:227], v150, s[42:43] offset:512
	global_load_dwordx4 v[228:231], v150, s[42:43] offset:528
	s_add_u32 s42, s42, 0x10000
	s_addc_u32 s43, s43, 0
	global_load_dwordx4 v[142:145], v150, s[42:43]
	global_load_dwordx4 v[146:149], v150, s[42:43] offset:16
	global_load_dwordx4 v[158:161], v150, s[42:43] offset:512
	global_load_dwordx4 v[204:207], v150, s[42:43] offset:528
	s_add_u32 s42, s42, 0x50000
	s_addc_u32 s43, s43, 0
	s_waitcnt vmcnt(12)
	v_pk_add_f32 v[126:127], v[126:127], v[168:169]
	v_pk_add_f32 v[128:129], v[128:129], v[170:171]
	v_pk_add_f32 v[122:123], v[122:123], v[172:173]
	v_pk_add_f32 v[124:125], v[124:125], v[174:175]
	v_pk_add_f32 v[118:119], v[118:119], v[176:177]
	v_pk_add_f32 v[120:121], v[120:121], v[178:179]
	v_pk_add_f32 v[114:115], v[114:115], v[180:181]
	v_pk_add_f32 v[116:117], v[116:117], v[182:183]
	v_cvt_pk_bf16_f32 v168, v126, v127
	v_cvt_pk_bf16_f32 v169, v128, v129
	v_cvt_pk_bf16_f32 v170, v122, v123
	v_cvt_pk_bf16_f32 v171, v124, v125
	v_cvt_pk_bf16_f32 v172, v118, v119
	v_cvt_pk_bf16_f32 v173, v120, v121
	v_cvt_pk_bf16_f32 v174, v114, v115
	v_cvt_pk_bf16_f32 v175, v116, v117
	ds_bpermute_b32 v168, v232, v168
	ds_bpermute_b32 v169, v232, v169
	ds_bpermute_b32 v170, v232, v170
	ds_bpermute_b32 v171, v232, v171
	ds_bpermute_b32 v172, v232, v172
	ds_bpermute_b32 v173, v232, v173
	ds_bpermute_b32 v174, v232, v174
	ds_bpermute_b32 v175, v232, v175
	v_mul_f32_e32 v163, v126, v126
	v_mul_f32_e32 v200, v127, v127
	v_fmac_f32_e32 v163, v128, v128
	v_fmac_f32_e32 v200, v129, v129
	v_fmac_f32_e32 v163, v122, v122
	v_fmac_f32_e32 v200, v123, v123
	v_fmac_f32_e32 v163, v124, v124
	v_fmac_f32_e32 v200, v125, v125
	v_fmac_f32_e32 v163, v118, v118
	v_fmac_f32_e32 v200, v119, v119
	v_fmac_f32_e32 v163, v120, v120
	v_fmac_f32_e32 v200, v121, v121
	v_fmac_f32_e32 v163, v114, v114
	v_fmac_f32_e32 v200, v115, v115
	v_fmac_f32_e32 v163, v116, v116
	v_fmac_f32_e32 v200, v117, v117
	global_store_dwordx4 v150, v[126:129], s[44:45]
	global_store_dwordx4 v150, v[122:125], s[44:45] offset:16
	global_store_dwordx4 v150, v[118:121], s[44:45] offset:512
	global_store_dwordx4 v150, v[114:117], s[44:45] offset:528
	s_waitcnt lgkmcnt(0)
	global_store_dwordx4 v234, v[168:171], s[6:7]
	global_store_dwordx4 v234, v[172:175], s[6:7] offset:256
	v_add_f32_e32 v114, v163, v200
	s_add_u32 s44, s44, 0x10000
	s_addc_u32 s45, s45, 0
	s_add_u32 s6, s6, 0x8000
	s_addc_u32 s7, s7, 0
	global_load_dwordx4 v[168:171], v150, s[42:43]
	global_load_dwordx4 v[172:175], v150, s[42:43] offset:16
	global_load_dwordx4 v[176:179], v150, s[42:43] offset:512
	global_load_dwordx4 v[180:183], v150, s[42:43] offset:528
	s_add_u32 s42, s42, 0x10000
	s_addc_u32 s43, s43, 0
	s_waitcnt vmcnt(18)
	v_pk_add_f32 v[110:111], v[110:111], v[184:185]
	v_pk_add_f32 v[112:113], v[112:113], v[186:187]
	v_pk_add_f32 v[106:107], v[106:107], v[188:189]
	v_pk_add_f32 v[108:109], v[108:109], v[190:191]
	v_pk_add_f32 v[102:103], v[102:103], v[192:193]
	v_pk_add_f32 v[104:105], v[104:105], v[194:195]
	v_pk_add_f32 v[98:99], v[98:99], v[196:197]
	v_pk_add_f32 v[100:101], v[100:101], v[198:199]
	v_cvt_pk_bf16_f32 v184, v110, v111
	v_cvt_pk_bf16_f32 v185, v112, v113
	v_cvt_pk_bf16_f32 v186, v106, v107
	v_cvt_pk_bf16_f32 v187, v108, v109
	v_cvt_pk_bf16_f32 v188, v102, v103
	v_cvt_pk_bf16_f32 v189, v104, v105
	v_cvt_pk_bf16_f32 v190, v98, v99
	v_cvt_pk_bf16_f32 v191, v100, v101
	ds_bpermute_b32 v184, v232, v184
	ds_bpermute_b32 v185, v232, v185
	ds_bpermute_b32 v186, v232, v186
	ds_bpermute_b32 v187, v232, v187
	ds_bpermute_b32 v188, v232, v188
	ds_bpermute_b32 v189, v232, v189
	ds_bpermute_b32 v190, v232, v190
	ds_bpermute_b32 v191, v232, v191
	v_mul_f32_e32 v163, v110, v110
	v_mul_f32_e32 v200, v111, v111
	v_fmac_f32_e32 v163, v112, v112
	v_fmac_f32_e32 v200, v113, v113
	v_fmac_f32_e32 v163, v106, v106
	v_fmac_f32_e32 v200, v107, v107
	v_fmac_f32_e32 v163, v108, v108
	v_fmac_f32_e32 v200, v109, v109
	v_fmac_f32_e32 v163, v102, v102
	v_fmac_f32_e32 v200, v103, v103
	v_fmac_f32_e32 v163, v104, v104
	v_fmac_f32_e32 v200, v105, v105
	v_fmac_f32_e32 v163, v98, v98
	v_fmac_f32_e32 v200, v99, v99
	v_fmac_f32_e32 v163, v100, v100
	v_fmac_f32_e32 v200, v101, v101
	global_store_dwordx4 v150, v[110:113], s[44:45]
	global_store_dwordx4 v150, v[106:109], s[44:45] offset:16
	global_store_dwordx4 v150, v[102:105], s[44:45] offset:512
	global_store_dwordx4 v150, v[98:101], s[44:45] offset:528
	s_waitcnt lgkmcnt(0)
; __device__ __forceinline__ unsigned cvtpk(float lo, float hi) { f32x2 v = {lo, hi}; bf16x2_t b = __builtin_convertvector(v, bf16x2_t); return __builtin_bit_cast(unsigned, b); }
;     __device__ __forceinline__ void operator()(const f32x4 (&acc)[2][2][4][2], const pg8::Unit& u, int wr, int wc, int fr, int fq) const {
;     ...
;                     for (int bj = 0; bj < 2; ++bj) {
;                         const int col0 = u.pn * 256 + bj * 128 + wc * 32 + 8 * fq;
;                         const f32x4 h0 = *(const f32x4*)(src + col0) + acc[ai][bj][m][0];
;                         const f32x4 h1 = *(const f32x4*)(src + col0 + 4) + acc[ai][bj][m][1];
;                         *(f32x4*)(dst + col0) = h0; *(f32x4*)(dst + col0 + 4) = h1;
;                         if (P) { u32x4 w; w.x = cvtpk(h0[0], h0[1]); w.y = cvtpk(h0[2], h0[3]); w.z = cvtpk(h1[0], h1[1]); w.w = cvtpk(h1[2], h1[3]);
;                             *(u32x4*)(P + (size_t)grow * DM + col0) = w; }
;                         ss += (h0[0] * h0[0] + h0[1] * h0[1]) + (h0[2] * h0[2] + h0[3] * h0[3]) + (h1[0] * h1[0] + h1[1] * h1[1]) + (h1[2] * h1[2] + h1[3] * h1[3]);
;                     }
	global_store_dwordx4 v234, v[184:187], s[6:7]
	global_store_dwordx4 v234, v[188:191], s[6:7] offset:256
	v_add_f32_e32 v98, v163, v200
	s_add_u32 s44, s44, 0x10000
	s_addc_u32 s45, s45, 0
	s_add_u32 s6, s6, 0x8000
	s_addc_u32 s7, s7, 0
	global_load_dwordx4 v[184:187], v150, s[42:43]
	global_load_dwordx4 v[188:191], v150, s[42:43] offset:16
	global_load_dwordx4 v[192:195], v150, s[42:43] offset:512
	global_load_dwordx4 v[196:199], v150, s[42:43] offset:528
	s_add_u32 s42, s42, 0x10000
	s_addc_u32 s43, s43, 0
	s_waitcnt vmcnt(24)
	v_pk_add_f32 v[94:95], v[94:95], v[216:217]
	v_pk_add_f32 v[96:97], v[96:97], v[218:219]
	v_pk_add_f32 v[90:91], v[90:91], v[220:221]
	v_pk_add_f32 v[92:93], v[92:93], v[222:223]
	v_pk_add_f32 v[86:87], v[86:87], v[224:225]
	v_pk_add_f32 v[88:89], v[88:89], v[226:227]
	v_pk_add_f32 v[82:83], v[82:83], v[228:229]
	v_pk_add_f32 v[84:85], v[84:85], v[230:231]
	v_cvt_pk_bf16_f32 v216, v94, v95
	v_cvt_pk_bf16_f32 v217, v96, v97
	v_cvt_pk_bf16_f32 v218, v90, v91
	v_cvt_pk_bf16_f32 v219, v92, v93
	v_cvt_pk_bf16_f32 v220, v86, v87
	v_cvt_pk_bf16_f32 v221, v88, v89
	v_cvt_pk_bf16_f32 v222, v82, v83
	v_cvt_pk_bf16_f32 v223, v84, v85
	ds_bpermute_b32 v216, v232, v216
	ds_bpermute_b32 v217, v232, v217
	ds_bpermute_b32 v218, v232, v218
	ds_bpermute_b32 v219, v232, v219
	ds_bpermute_b32 v220, v232, v220
	ds_bpermute_b32 v221, v232, v221
	ds_bpermute_b32 v222, v232, v222
	ds_bpermute_b32 v223, v232, v223
	v_mul_f32_e32 v163, v94, v94
	v_mul_f32_e32 v200, v95, v95
	v_fmac_f32_e32 v163, v96, v96
	v_fmac_f32_e32 v200, v97, v97
	v_fmac_f32_e32 v163, v90, v90
	v_fmac_f32_e32 v200, v91, v91
	v_fmac_f32_e32 v163, v92, v92
	v_fmac_f32_e32 v200, v93, v93
	v_fmac_f32_e32 v163, v86, v86
	v_fmac_f32_e32 v200, v87, v87
	v_fmac_f32_e32 v163, v88, v88
	v_fmac_f32_e32 v200, v89, v89
	v_fmac_f32_e32 v163, v82, v82
	v_fmac_f32_e32 v200, v83, v83
	v_fmac_f32_e32 v163, v84, v84
	v_fmac_f32_e32 v200, v85, v85
	global_store_dwordx4 v150, v[94:97], s[44:45]
	global_store_dwordx4 v150, v[90:93], s[44:45] offset:16
	global_store_dwordx4 v150, v[86:89], s[44:45] offset:512
	global_store_dwordx4 v150, v[82:85], s[44:45] offset:528
	s_waitcnt lgkmcnt(0)
	global_store_dwordx4 v234, v[216:219], s[6:7]
	global_store_dwordx4 v234, v[220:223], s[6:7] offset:256
	v_add_f32_e32 v82, v163, v200
	s_add_u32 s44, s44, 0x10000
	s_addc_u32 s45, s45, 0
	s_add_u32 s6, s6, 0x8000
	s_addc_u32 s7, s7, 0
	global_load_dwordx4 v[216:219], v150, s[42:43]
	global_load_dwordx4 v[220:223], v150, s[42:43] offset:16
	global_load_dwordx4 v[224:227], v150, s[42:43] offset:512
	global_load_dwordx4 v[228:231], v150, s[42:43] offset:528
	s_add_u32 s42, s42, 0x10000
	s_addc_u32 s43, s43, 0
	s_waitcnt vmcnt(30)
	v_pk_add_f32 v[78:79], v[78:79], v[142:143]
	v_pk_add_f32 v[80:81], v[80:81], v[144:145]
	v_pk_add_f32 v[74:75], v[74:75], v[146:147]
	v_pk_add_f32 v[76:77], v[76:77], v[148:149]
	v_pk_add_f32 v[70:71], v[70:71], v[158:159]
	v_pk_add_f32 v[72:73], v[72:73], v[160:161]
	v_pk_add_f32 v[66:67], v[66:67], v[204:205]
	v_pk_add_f32 v[68:69], v[68:69], v[206:207]
	v_cvt_pk_bf16_f32 v142, v78, v79
	v_cvt_pk_bf16_f32 v143, v80, v81
	v_cvt_pk_bf16_f32 v144, v74, v75
	v_cvt_pk_bf16_f32 v145, v76, v77
	v_cvt_pk_bf16_f32 v146, v70, v71
	v_cvt_pk_bf16_f32 v147, v72, v73
	v_cvt_pk_bf16_f32 v148, v66, v67
	v_cvt_pk_bf16_f32 v149, v68, v69
	ds_bpermute_b32 v142, v232, v142
	ds_bpermute_b32 v143, v232, v143
	ds_bpermute_b32 v144, v232, v144
	ds_bpermute_b32 v145, v232, v145
	ds_bpermute_b32 v146, v232, v146
	ds_bpermute_b32 v147, v232, v147
	ds_bpermute_b32 v148, v232, v148
	ds_bpermute_b32 v149, v232, v149
	v_mul_f32_e32 v163, v78, v78
	v_mul_f32_e32 v200, v79, v79
	v_fmac_f32_e32 v163, v80, v80
	v_fmac_f32_e32 v200, v81, v81
	v_fmac_f32_e32 v163, v74, v74
	v_fmac_f32_e32 v200, v75, v75
	v_fmac_f32_e32 v163, v76, v76
	v_fmac_f32_e32 v200, v77, v77
	v_fmac_f32_e32 v163, v70, v70
	v_fmac_f32_e32 v200, v71, v71
	v_fmac_f32_e32 v163, v72, v72
	v_fmac_f32_e32 v200, v73, v73
	v_fmac_f32_e32 v163, v66, v66
	v_fmac_f32_e32 v200, v67, v67
	v_fmac_f32_e32 v163, v68, v68
	v_fmac_f32_e32 v200, v69, v69
	global_store_dwordx4 v150, v[78:81], s[44:45]
	global_store_dwordx4 v150, v[74:77], s[44:45] offset:16
	global_store_dwordx4 v150, v[70:73], s[44:45] offset:512
	global_store_dwordx4 v150, v[66:69], s[44:45] offset:528
	s_waitcnt lgkmcnt(0)
	global_store_dwordx4 v234, v[142:145], s[6:7]
	global_store_dwordx4 v234, v[146:149], s[6:7] offset:256
	v_add_f32_e32 v66, v163, v200
	s_add_u32 s44, s44, 0x50000
	s_addc_u32 s45, s45, 0
	s_add_u32 s6, s6, 0x28000
	s_addc_u32 s7, s7, 0
	global_load_dwordx4 v[142:145], v150, s[42:43]
	global_load_dwordx4 v[146:149], v150, s[42:43] offset:16
	global_load_dwordx4 v[158:161], v150, s[42:43] offset:512
	global_load_dwordx4 v[204:207], v150, s[42:43] offset:528
	s_waitcnt vmcnt(30)
; __device__ __forceinline__ unsigned cvtpk(float lo, float hi) { f32x2 v = {lo, hi}; bf16x2_t b = __builtin_convertvector(v, bf16x2_t); return __builtin_bit_cast(unsigned, b); }
;     __device__ __forceinline__ void operator()(const f32x4 (&acc)[2][2][4][2], const pg8::Unit& u, int wr, int wc, int fr, int fq) const {
;     ...
;                     for (int bj = 0; bj < 2; ++bj) {
;                         const int col0 = u.pn * 256 + bj * 128 + wc * 32 + 8 * fq;
;                         const f32x4 h0 = *(const f32x4*)(src + col0) + acc[ai][bj][m][0];
;                         const f32x4 h1 = *(const f32x4*)(src + col0 + 4) + acc[ai][bj][m][1];
;                         *(f32x4*)(dst + col0) = h0; *(f32x4*)(dst + col0 + 4) = h1;
;                         if (P) { u32x4 w; w.x = cvtpk(h0[0], h0[1]); w.y = cvtpk(h0[2], h0[3]); w.z = cvtpk(h1[0], h1[1]); w.w = cvtpk(h1[2], h1[3]);
;                             *(u32x4*)(P + (size_t)grow * DM + col0) = w; }
;                         ss += (h0[0] * h0[0] + h0[1] * h0[1]) + (h0[2] * h0[2] + h0[3] * h0[3]) + (h1[0] * h1[0] + h1[1] * h1[1]) + (h1[2] * h1[2] + h1[3] * h1[3]);
;                     }
	v_pk_add_f32 v[62:63], v[62:63], v[168:169]
	v_pk_add_f32 v[64:65], v[64:65], v[170:171]
	v_pk_add_f32 v[58:59], v[58:59], v[172:173]
	v_pk_add_f32 v[60:61], v[60:61], v[174:175]
	v_pk_add_f32 v[54:55], v[54:55], v[176:177]
	v_pk_add_f32 v[56:57], v[56:57], v[178:179]
	v_pk_add_f32 v[50:51], v[50:51], v[180:181]
	v_pk_add_f32 v[52:53], v[52:53], v[182:183]
	v_cvt_pk_bf16_f32 v168, v62, v63
	v_cvt_pk_bf16_f32 v169, v64, v65
	v_cvt_pk_bf16_f32 v170, v58, v59
	v_cvt_pk_bf16_f32 v171, v60, v61
	v_cvt_pk_bf16_f32 v172, v54, v55
	v_cvt_pk_bf16_f32 v173, v56, v57
	v_cvt_pk_bf16_f32 v174, v50, v51
	v_cvt_pk_bf16_f32 v175, v52, v53
	ds_bpermute_b32 v168, v232, v168
	ds_bpermute_b32 v169, v232, v169
	ds_bpermute_b32 v170, v232, v170
	ds_bpermute_b32 v171, v232, v171
	ds_bpermute_b32 v172, v232, v172
	ds_bpermute_b32 v173, v232, v173
	ds_bpermute_b32 v174, v232, v174
	ds_bpermute_b32 v175, v232, v175
	v_mul_f32_e32 v163, v62, v62
	v_mul_f32_e32 v200, v63, v63
	v_fmac_f32_e32 v163, v64, v64
	v_fmac_f32_e32 v200, v65, v65
	v_fmac_f32_e32 v163, v58, v58
	v_fmac_f32_e32 v200, v59, v59
	v_fmac_f32_e32 v163, v60, v60
	v_fmac_f32_e32 v200, v61, v61
	v_fmac_f32_e32 v163, v54, v54
	v_fmac_f32_e32 v200, v55, v55
	v_fmac_f32_e32 v163, v56, v56
	v_fmac_f32_e32 v200, v57, v57
	v_fmac_f32_e32 v163, v50, v50
	v_fmac_f32_e32 v200, v51, v51
	v_fmac_f32_e32 v163, v52, v52
	v_fmac_f32_e32 v200, v53, v53
	global_store_dwordx4 v150, v[62:65], s[44:45]
	global_store_dwordx4 v150, v[58:61], s[44:45] offset:16
	global_store_dwordx4 v150, v[54:57], s[44:45] offset:512
	global_store_dwordx4 v150, v[50:53], s[44:45] offset:528
	s_waitcnt lgkmcnt(0)
	global_store_dwordx4 v234, v[168:171], s[6:7]
	global_store_dwordx4 v234, v[172:175], s[6:7] offset:256
	v_add_f32_e32 v50, v163, v200
	s_add_u32 s44, s44, 0x10000
	s_addc_u32 s45, s45, 0
	s_add_u32 s6, s6, 0x8000
	s_addc_u32 s7, s7, 0
	s_waitcnt vmcnt(26)
	v_pk_add_f32 v[46:47], v[46:47], v[184:185]
	v_pk_add_f32 v[48:49], v[48:49], v[186:187]
	v_pk_add_f32 v[42:43], v[42:43], v[188:189]
	v_pk_add_f32 v[44:45], v[44:45], v[190:191]
	v_pk_add_f32 v[38:39], v[38:39], v[192:193]
	v_pk_add_f32 v[40:41], v[40:41], v[194:195]
	v_pk_add_f32 v[34:35], v[34:35], v[196:197]
	v_pk_add_f32 v[36:37], v[36:37], v[198:199]
	v_cvt_pk_bf16_f32 v184, v46, v47
	v_cvt_pk_bf16_f32 v185, v48, v49
	v_cvt_pk_bf16_f32 v186, v42, v43
	v_cvt_pk_bf16_f32 v187, v44, v45
	v_cvt_pk_bf16_f32 v188, v38, v39
	v_cvt_pk_bf16_f32 v189, v40, v41
	v_cvt_pk_bf16_f32 v190, v34, v35
	v_cvt_pk_bf16_f32 v191, v36, v37
	ds_bpermute_b32 v184, v232, v184
	ds_bpermute_b32 v185, v232, v185
	ds_bpermute_b32 v186, v232, v186
	ds_bpermute_b32 v187, v232, v187
	ds_bpermute_b32 v188, v232, v188
	ds_bpermute_b32 v189, v232, v189
	ds_bpermute_b32 v190, v232, v190
	ds_bpermute_b32 v191, v232, v191
	v_mul_f32_e32 v163, v46, v46
	v_mul_f32_e32 v200, v47, v47
	v_fmac_f32_e32 v163, v48, v48
	v_fmac_f32_e32 v200, v49, v49
	v_fmac_f32_e32 v163, v42, v42
	v_fmac_f32_e32 v200, v43, v43
	v_fmac_f32_e32 v163, v44, v44
	v_fmac_f32_e32 v200, v45, v45
	v_fmac_f32_e32 v163, v38, v38
	v_fmac_f32_e32 v200, v39, v39
	v_fmac_f32_e32 v163, v40, v40
	v_fmac_f32_e32 v200, v41, v41
	v_fmac_f32_e32 v163, v34, v34
	v_fmac_f32_e32 v200, v35, v35
	v_fmac_f32_e32 v163, v36, v36
	v_fmac_f32_e32 v200, v37, v37
	global_store_dwordx4 v150, v[46:49], s[44:45]
	global_store_dwordx4 v150, v[42:45], s[44:45] offset:16
	global_store_dwordx4 v150, v[38:41], s[44:45] offset:512
	global_store_dwordx4 v150, v[34:37], s[44:45] offset:528
	s_waitcnt lgkmcnt(0)
	global_store_dwordx4 v234, v[184:187], s[6:7]
	global_store_dwordx4 v234, v[188:191], s[6:7] offset:256
	v_add_f32_e32 v34, v163, v200
	s_add_u32 s44, s44, 0x10000
	s_addc_u32 s45, s45, 0
	s_add_u32 s6, s6, 0x8000
	s_addc_u32 s7, s7, 0
	s_waitcnt vmcnt(22)
	v_pk_add_f32 v[28:29], v[28:29], v[216:217]
	v_pk_add_f32 v[30:31], v[30:31], v[218:219]
	v_pk_add_f32 v[24:25], v[24:25], v[220:221]
	v_pk_add_f32 v[26:27], v[26:27], v[222:223]
	v_pk_add_f32 v[20:21], v[20:21], v[224:225]
	v_pk_add_f32 v[22:23], v[22:23], v[226:227]
	v_pk_add_f32 v[16:17], v[16:17], v[228:229]
	v_pk_add_f32 v[18:19], v[18:19], v[230:231]
	v_cvt_pk_bf16_f32 v216, v28, v29
	v_cvt_pk_bf16_f32 v217, v30, v31
	v_cvt_pk_bf16_f32 v218, v24, v25
	v_cvt_pk_bf16_f32 v219, v26, v27
	v_cvt_pk_bf16_f32 v220, v20, v21
	v_cvt_pk_bf16_f32 v221, v22, v23
	v_cvt_pk_bf16_f32 v222, v16, v17
	v_cvt_pk_bf16_f32 v223, v18, v19
	ds_bpermute_b32 v216, v232, v216
	ds_bpermute_b32 v217, v232, v217
	ds_bpermute_b32 v218, v232, v218
	ds_bpermute_b32 v219, v232, v219
	ds_bpermute_b32 v220, v232, v220
	ds_bpermute_b32 v221, v232, v221
	ds_bpermute_b32 v222, v232, v222
	ds_bpermute_b32 v223, v232, v223
	v_mul_f32_e32 v163, v28, v28
	v_mul_f32_e32 v200, v29, v29
	v_fmac_f32_e32 v163, v30, v30
	v_fmac_f32_e32 v200, v31, v31
	v_fmac_f32_e32 v163, v24, v24
	v_fmac_f32_e32 v200, v25, v25
	v_fmac_f32_e32 v163, v26, v26
	v_fmac_f32_e32 v200, v27, v27
	v_fmac_f32_e32 v163, v20, v20
	v_fmac_f32_e32 v200, v21, v21
	v_fmac_f32_e32 v163, v22, v22
	v_fmac_f32_e32 v200, v23, v23
	v_fmac_f32_e32 v163, v16, v16
	v_fmac_f32_e32 v200, v17, v17
	v_fmac_f32_e32 v163, v18, v18
	v_fmac_f32_e32 v200, v19, v19
	global_store_dwordx4 v150, v[28:31], s[44:45]
	global_store_dwordx4 v150, v[24:27], s[44:45] offset:16
	global_store_dwordx4 v150, v[20:23], s[44:45] offset:512
	global_store_dwordx4 v150, v[16:19], s[44:45] offset:528
	s_waitcnt lgkmcnt(0)
; __device__ __forceinline__ unsigned cvtpk(float lo, float hi) { f32x2 v = {lo, hi}; bf16x2_t b = __builtin_convertvector(v, bf16x2_t); return __builtin_bit_cast(unsigned, b); }
;     __device__ __forceinline__ void operator()(const f32x4 (&acc)[2][2][4][2], const pg8::Unit& u, int wr, int wc, int fr, int fq) const {
;     ...
;                     for (int bj = 0; bj < 2; ++bj) {
;                         const int col0 = u.pn * 256 + bj * 128 + wc * 32 + 8 * fq;
;                         const f32x4 h0 = *(const f32x4*)(src + col0) + acc[ai][bj][m][0];
;                         const f32x4 h1 = *(const f32x4*)(src + col0 + 4) + acc[ai][bj][m][1];
;                         *(f32x4*)(dst + col0) = h0; *(f32x4*)(dst + col0 + 4) = h1;
;                         if (P) { u32x4 w; w.x = cvtpk(h0[0], h0[1]); w.y = cvtpk(h0[2], h0[3]); w.z = cvtpk(h1[0], h1[1]); w.w = cvtpk(h1[2], h1[3]);
;                             *(u32x4*)(P + (size_t)grow * DM + col0) = w; }
;                         ss += (h0[0] * h0[0] + h0[1] * h0[1]) + (h0[2] * h0[2] + h0[3] * h0[3]) + (h1[0] * h1[0] + h1[1] * h1[1]) + (h1[2] * h1[2] + h1[3] * h1[3]);
;                     }
;                 }
;                 ss += __shfl_xor(ss, 16); ss += __shfl_xor(ss, 32);
;                 if (ok && fq == 0 && rowss_next) atomicAdd(rowss_next + grow, (u64)(ss * SS_SCALE));
	global_store_dwordx4 v234, v[216:219], s[6:7]
	global_store_dwordx4 v234, v[220:223], s[6:7] offset:256
	v_add_f32_e32 v16, v163, v200
	s_add_u32 s44, s44, 0x10000
	s_addc_u32 s45, s45, 0
	s_add_u32 s6, s6, 0x8000
	s_addc_u32 s7, s7, 0
	s_waitcnt vmcnt(18)
	v_pk_add_f32 v[12:13], v[12:13], v[142:143]
	v_pk_add_f32 v[14:15], v[14:15], v[144:145]
	v_pk_add_f32 v[8:9], v[8:9], v[146:147]
	v_pk_add_f32 v[10:11], v[10:11], v[148:149]
	v_pk_add_f32 v[4:5], v[4:5], v[158:159]
	v_pk_add_f32 v[6:7], v[6:7], v[160:161]
	v_pk_add_f32 v[0:1], v[0:1], v[204:205]
	v_pk_add_f32 v[2:3], v[2:3], v[206:207]
	v_cvt_pk_bf16_f32 v142, v12, v13
	v_cvt_pk_bf16_f32 v143, v14, v15
	v_cvt_pk_bf16_f32 v144, v8, v9
	v_cvt_pk_bf16_f32 v145, v10, v11
	v_cvt_pk_bf16_f32 v146, v4, v5
	v_cvt_pk_bf16_f32 v147, v6, v7
	v_cvt_pk_bf16_f32 v148, v0, v1
	v_cvt_pk_bf16_f32 v149, v2, v3
	ds_bpermute_b32 v142, v232, v142
	ds_bpermute_b32 v143, v232, v143
	ds_bpermute_b32 v144, v232, v144
	ds_bpermute_b32 v145, v232, v145
	ds_bpermute_b32 v146, v232, v146
	ds_bpermute_b32 v147, v232, v147
	ds_bpermute_b32 v148, v232, v148
	ds_bpermute_b32 v149, v232, v149
	v_mul_f32_e32 v163, v12, v12
	v_mul_f32_e32 v200, v13, v13
	v_fmac_f32_e32 v163, v14, v14
	v_fmac_f32_e32 v200, v15, v15
	v_fmac_f32_e32 v163, v8, v8
	v_fmac_f32_e32 v200, v9, v9
	v_fmac_f32_e32 v163, v10, v10
	v_fmac_f32_e32 v200, v11, v11
	v_fmac_f32_e32 v163, v4, v4
	v_fmac_f32_e32 v200, v5, v5
	v_fmac_f32_e32 v163, v6, v6
	v_fmac_f32_e32 v200, v7, v7
	v_fmac_f32_e32 v163, v0, v0
	v_fmac_f32_e32 v200, v1, v1
	v_fmac_f32_e32 v163, v2, v2
	v_fmac_f32_e32 v200, v3, v3
	global_store_dwordx4 v150, v[12:15], s[44:45]
	global_store_dwordx4 v150, v[8:11], s[44:45] offset:16
	global_store_dwordx4 v150, v[4:7], s[44:45] offset:512
	global_store_dwordx4 v150, v[0:3], s[44:45] offset:528
	s_waitcnt lgkmcnt(0)
	global_store_dwordx4 v234, v[142:145], s[6:7]
	global_store_dwordx4 v234, v[146:149], s[6:7] offset:256
	v_add_f32_e32 v0, v163, v200
	v_mbcnt_lo_u32_b32 v201, -1, 0
	v_mbcnt_hi_u32_b32 v201, -1, v201
	v_xor_b32_e32 v208, 16, v201
	v_xor_b32_e32 v209, 32, v201
	v_lshlrev_b32_e32 v208, 2, v208
	v_lshlrev_b32_e32 v209, 2, v209
	ds_bpermute_b32 v115, v208, v114
	ds_bpermute_b32 v99, v208, v98
	ds_bpermute_b32 v83, v208, v82
	ds_bpermute_b32 v67, v208, v66
	ds_bpermute_b32 v51, v208, v50
	ds_bpermute_b32 v35, v208, v34
	ds_bpermute_b32 v17, v208, v16
	ds_bpermute_b32 v1, v208, v0
	s_waitcnt lgkmcnt(0)
	v_add_f32_e32 v114, v114, v115
	v_add_f32_e32 v98, v98, v99
	v_add_f32_e32 v82, v82, v83
	v_add_f32_e32 v66, v66, v67
	v_add_f32_e32 v50, v50, v51
	v_add_f32_e32 v34, v34, v35
	v_add_f32_e32 v16, v16, v17
	v_add_f32_e32 v0, v0, v1
	ds_bpermute_b32 v115, v209, v114
	ds_bpermute_b32 v99, v209, v98
	ds_bpermute_b32 v83, v209, v82
	ds_bpermute_b32 v67, v209, v66
	ds_bpermute_b32 v51, v209, v50
	ds_bpermute_b32 v35, v209, v34
	ds_bpermute_b32 v17, v209, v16
	ds_bpermute_b32 v1, v209, v0
	s_waitcnt lgkmcnt(0)
	v_add_f32_e32 v114, v114, v115
	v_add_f32_e32 v98, v98, v99
	v_add_f32_e32 v82, v82, v83
	v_add_f32_e32 v66, v66, v67
	v_add_f32_e32 v50, v50, v51
	v_add_f32_e32 v34, v34, v35
	v_add_f32_e32 v16, v16, v17
	v_add_f32_e32 v0, v0, v1
	s_and_saveexec_b64 s[42:43], s[2:3]
	v_mul_f32_e32 v114, 0x49800000, v114
	v_trunc_f32_e32 v114, v114
	v_mul_f32_e32 v115, 0x2f800000, v114
	v_floor_f32_e32 v115, v115
	v_fmac_f32_e32 v114, 0xcf800000, v115
	v_cvt_u32_f32_e32 v116, v114
	v_cvt_u32_f32_e32 v117, v115
	global_atomic_add_x2 v162, v[116:117], s[8:9]
	v_mul_f32_e32 v98, 0x49800000, v98
	v_trunc_f32_e32 v98, v98
	v_mul_f32_e32 v99, 0x2f800000, v98
	v_floor_f32_e32 v99, v99
	v_fmac_f32_e32 v98, 0xcf800000, v99
	v_cvt_u32_f32_e32 v100, v98
	v_cvt_u32_f32_e32 v101, v99
	global_atomic_add_x2 v162, v[100:101], s[8:9] offset:128
	v_mul_f32_e32 v82, 0x49800000, v82
	v_trunc_f32_e32 v82, v82
	v_mul_f32_e32 v83, 0x2f800000, v82
	v_floor_f32_e32 v83, v83
	v_fmac_f32_e32 v82, 0xcf800000, v83
	v_cvt_u32_f32_e32 v84, v82
	v_cvt_u32_f32_e32 v85, v83
	global_atomic_add_x2 v162, v[84:85], s[8:9] offset:256
	v_mul_f32_e32 v66, 0x49800000, v66
	v_trunc_f32_e32 v66, v66
	v_mul_f32_e32 v67, 0x2f800000, v66
	v_floor_f32_e32 v67, v67
	v_fmac_f32_e32 v66, 0xcf800000, v67
	v_cvt_u32_f32_e32 v68, v66
	v_cvt_u32_f32_e32 v69, v67
	global_atomic_add_x2 v162, v[68:69], s[8:9] offset:384
	v_mul_f32_e32 v50, 0x49800000, v50
	v_trunc_f32_e32 v50, v50
	v_mul_f32_e32 v51, 0x2f800000, v50
	v_floor_f32_e32 v51, v51
	v_fmac_f32_e32 v50, 0xcf800000, v51
	v_cvt_u32_f32_e32 v52, v50
	v_cvt_u32_f32_e32 v53, v51
	global_atomic_add_x2 v162, v[52:53], s[8:9] offset:1024
	v_mul_f32_e32 v34, 0x49800000, v34
	v_trunc_f32_e32 v34, v34
	v_mul_f32_e32 v35, 0x2f800000, v34
	v_floor_f32_e32 v35, v35
	v_fmac_f32_e32 v34, 0xcf800000, v35
	v_cvt_u32_f32_e32 v36, v34
	v_cvt_u32_f32_e32 v37, v35
	global_atomic_add_x2 v162, v[36:37], s[8:9] offset:1152
	v_mul_f32_e32 v16, 0x49800000, v16
	v_trunc_f32_e32 v16, v16
	v_mul_f32_e32 v17, 0x2f800000, v16
	v_floor_f32_e32 v17, v17
	v_fmac_f32_e32 v16, 0xcf800000, v17
	v_cvt_u32_f32_e32 v18, v16
	v_cvt_u32_f32_e32 v19, v17
	global_atomic_add_x2 v162, v[18:19], s[8:9] offset:1280
	v_mul_f32_e32 v0, 0x49800000, v0
	v_trunc_f32_e32 v0, v0
	v_mul_f32_e32 v1, 0x2f800000, v0
	v_floor_f32_e32 v1, v1
	v_fmac_f32_e32 v0, 0xcf800000, v1
	v_cvt_u32_f32_e32 v2, v0
	v_cvt_u32_f32_e32 v3, v1
	global_atomic_add_x2 v162, v[2:3], s[8:9] offset:1408
	s_mov_b64 exec, s[42:43]
	s_movk_i32 s75, 0x80
	s_mov_b32 s76, 0x7f807f81
	s_movk_i32 s77, 0x5b
	s_branch .Lepi_done_ao

; __device__ __forceinline__ unsigned cvtpk(float lo, float hi) { f32x2 v = {lo, hi}; bf16x2_t b = __builtin_convertvector(v, bf16x2_t); return __builtin_bit_cast(unsigned, b); }
;     __device__ __forceinline__ void operator()(const f32x4 (&acc)[2][2][4][2], const pg8::Unit& u, int wr, int wc, int fr, int fq) const {
;     ...
;                 const int grow = row_base + u.pm * 256 + ai * 128 + wr * 64 + m * 16 + fr;
;                 const bool ok = grow < MREAL;
;                 float ss = 0.f;
;                 if (ok) {
;                     const float* src; float* dst;
;                     if (grow < ROWS_P) { src = srcA + (size_t)grow * DM; dst = dstMain + (size_t)grow * DM; }
;                     else if (grow < ROWS_MAIN) { src = srcB + (size_t)(grow - ROWS_P) * DM; dst = dstMain + (size_t)grow * DM; }
;                     else { const int mr = grow - ROWS_MAIN; src = srcM + (size_t)(mr & meta_mask) * DM; dst = dstM + (size_t)mr * DM; }
; #pragma unroll
;                     for (int bj = 0; bj < 2; ++bj) {
;                         const int col0 = u.pn * 256 + bj * 128 + wc * 32 + 8 * fq;
;                         const f32x4 h0 = *(const f32x4*)(src + col0) + acc[ai][bj][m][0];
;                         const f32x4 h1 = *(const f32x4*)(src + col0 + 4) + acc[ai][bj][m][1];
;                         *(f32x4*)(dst + col0) = h0; *(f32x4*)(dst + col0 + 4) = h1;
;                         if (P) { u32x4 w; w.x = cvtpk(h0[0], h0[1]); w.y = cvtpk(h0[2], h0[3]); w.z = cvtpk(h1[0], h1[1]); w.w = cvtpk(h1[2], h1[3]);
;                             *(u32x4*)(P + (size_t)grow * DM + col0) = w; }
;                         ss += (h0[0] * h0[0] + h0[1] * h0[1]) + (h0[2] * h0[2] + h0[3] * h0[3]) + (h1[0] * h1[0] + h1[1] * h1[1]) + (h1[2] * h1[2] + h1[3] * h1[3]);
;                     }
.LBB0_2135:
	s_lshl_b32 vcc_lo, s8, 8
	s_add_i32 vcc_lo, vcc_lo, s66
	s_cmp_lt_u32 vcc_lo, 0x18000
	s_cbranch_scc0 .Lepi_old_dn
	s_cmp_lg_u64 s[18:19], 0
	s_cbranch_scc0 .Lepi_old_dn
	s_cmp_eq_u64 s[16:17], 0
	s_cbranch_scc0 .Lepi_old_dn
	s_lshl_b32 vcc_hi, s6, 10
	s_lshl_b32 s8, vcc_lo, 3
	s_add_u32 s8, s34, s8
	s_addc_u32 s9, s35, 0
	s_lshl_b32 s6, vcc_lo, 12
	s_add_u32 vcc_hi, vcc_hi, s6
	s_add_u32 s50, s12, vcc_hi
	s_addc_u32 s51, s13, 0
	s_lshr_b32 s6, vcc_hi, 1
	s_add_u32 s6, s30, s6
	s_addc_u32 s7, s31, 0
	s_cmp_lt_u32 vcc_lo, 0x8000
	s_cselect_b32 s48, s12, s36
	s_cselect_b32 s49, s13, s37
	s_cselect_b32 vcc_lo, 0, 0x8000000
	s_sub_u32 vcc_hi, vcc_hi, vcc_lo
	s_add_u32 s48, s48, vcc_hi
	s_addc_u32 s49, s49, 0
	v_lshlrev_b32_e32 v150, 12, v164
	v_lshl_add_u32 v150, v166, 2, v150
	v_lshrrev_b32_e32 v151, 1, v150
	v_lshlrev_b32_e32 v162, 3, v164
	v_mbcnt_lo_u32_b32 v235, -1, 0
	v_mbcnt_hi_u32_b32 v235, -1, v235
	v_and_b32_e32 v232, 3, v235
	v_lshlrev_b32_e32 v232, 6, v232
	v_and_b32_e32 v236, 60, v235
	v_or_b32_e32 v232, v232, v236
	v_lshrrev_b32_e32 v236, 2, v235
	v_and_b32_e32 v237, 15, v235
	v_sub_u32_e32 v236, v236, v237
	v_lshl_add_u32 v233, v236, 12, v150
	v_and_b32_e32 v236, 3, v235
	v_lshrrev_b32_e32 v237, 4, v235
	v_sub_u32_e32 v236, v236, v237
	v_lshl_add_u32 v233, v236, 5, v233
	v_lshrrev_b32_e32 v234, 1, v233
	global_load_dwordx4 v[168:171], v150, s[48:49]
	global_load_dwordx4 v[172:175], v150, s[48:49] offset:16
	global_load_dwordx4 v[176:179], v150, s[48:49] offset:512
	global_load_dwordx4 v[180:183], v150, s[48:49] offset:528
	s_add_u32 s48, s48, 0x10000
	s_addc_u32 s49, s49, 0
	global_load_dwordx4 v[184:187], v150, s[48:49]
	global_load_dwordx4 v[188:191], v150, s[48:49] offset:16
	global_load_dwordx4 v[192:195], v150, s[48:49] offset:512
	global_load_dwordx4 v[196:199], v150, s[48:49] offset:528
	s_add_u32 s48, s48, 0x10000
	s_addc_u32 s49, s49, 0
	global_load_dwordx4 v[216:219], v150, s[48:49]
	global_load_dwordx4 v[220:223], v150, s[48:49] offset:16
	global_load_dwordx4 v[224:227], v150, s[48:49] offset:512
	global_load_dwordx4 v[228:231], v150, s[48:49] offset:528
	s_add_u32 s48, s48, 0x10000
	s_addc_u32 s49, s49, 0
	global_load_dwordx4 v[142:145], v150, s[48:49]
	global_load_dwordx4 v[146:149], v150, s[48:49] offset:16
	global_load_dwordx4 v[158:161], v150, s[48:49] offset:512
	global_load_dwordx4 v[204:207], v150, s[48:49] offset:528
	s_add_u32 s48, s48, 0x50000
	s_addc_u32 s49, s49, 0
	s_waitcnt vmcnt(12)
	v_pk_add_f32 v[126:127], v[126:127], v[168:169]
	v_pk_add_f32 v[128:129], v[128:129], v[170:171]
	v_pk_add_f32 v[122:123], v[122:123], v[172:173]
	v_pk_add_f32 v[124:125], v[124:125], v[174:175]
	v_pk_add_f32 v[118:119], v[118:119], v[176:177]
	v_pk_add_f32 v[120:121], v[120:121], v[178:179]
	v_pk_add_f32 v[114:115], v[114:115], v[180:181]
	v_pk_add_f32 v[116:117], v[116:117], v[182:183]
	v_cvt_pk_bf16_f32 v168, v126, v127
	v_cvt_pk_bf16_f32 v169, v128, v129
	v_cvt_pk_bf16_f32 v170, v122, v123
	v_cvt_pk_bf16_f32 v171, v124, v125
	v_cvt_pk_bf16_f32 v172, v118, v119
	v_cvt_pk_bf16_f32 v173, v120, v121
	v_cvt_pk_bf16_f32 v174, v114, v115
	v_cvt_pk_bf16_f32 v175, v116, v117
	ds_bpermute_b32 v168, v232, v168
	ds_bpermute_b32 v169, v232, v169
	ds_bpermute_b32 v170, v232, v170
	ds_bpermute_b32 v171, v232, v171
	ds_bpermute_b32 v172, v232, v172
	ds_bpermute_b32 v173, v232, v173
	ds_bpermute_b32 v174, v232, v174
	ds_bpermute_b32 v175, v232, v175
	v_mul_f32_e32 v163, v126, v126
	v_mul_f32_e32 v200, v127, v127
	v_fmac_f32_e32 v163, v128, v128
	v_fmac_f32_e32 v200, v129, v129
	v_fmac_f32_e32 v163, v122, v122
	v_fmac_f32_e32 v200, v123, v123
	v_fmac_f32_e32 v163, v124, v124
	v_fmac_f32_e32 v200, v125, v125
	v_fmac_f32_e32 v163, v118, v118
	v_fmac_f32_e32 v200, v119, v119
	v_fmac_f32_e32 v163, v120, v120
	v_fmac_f32_e32 v200, v121, v121
	v_fmac_f32_e32 v163, v114, v114
	v_fmac_f32_e32 v200, v115, v115
	v_fmac_f32_e32 v163, v116, v116
	v_fmac_f32_e32 v200, v117, v117
	global_store_dwordx4 v150, v[126:129], s[50:51]
	global_store_dwordx4 v150, v[122:125], s[50:51] offset:16
	global_store_dwordx4 v150, v[118:121], s[50:51] offset:512
	global_store_dwordx4 v150, v[114:117], s[50:51] offset:528
	s_waitcnt lgkmcnt(0)
	global_store_dwordx4 v234, v[168:171], s[6:7]
	global_store_dwordx4 v234, v[172:175], s[6:7] offset:256
	v_add_f32_e32 v114, v163, v200
	s_add_u32 s50, s50, 0x10000
	s_addc_u32 s51, s51, 0
	s_add_u32 s6, s6, 0x8000
	s_addc_u32 s7, s7, 0
	global_load_dwordx4 v[168:171], v150, s[48:49]
	global_load_dwordx4 v[172:175], v150, s[48:49] offset:16
	global_load_dwordx4 v[176:179], v150, s[48:49] offset:512
	global_load_dwordx4 v[180:183], v150, s[48:49] offset:528
	s_add_u32 s48, s48, 0x10000
	s_addc_u32 s49, s49, 0
	s_waitcnt vmcnt(18)
	v_pk_add_f32 v[110:111], v[110:111], v[184:185]
	v_pk_add_f32 v[112:113], v[112:113], v[186:187]
	v_pk_add_f32 v[106:107], v[106:107], v[188:189]
	v_pk_add_f32 v[108:109], v[108:109], v[190:191]
	v_pk_add_f32 v[102:103], v[102:103], v[192:193]
	v_pk_add_f32 v[104:105], v[104:105], v[194:195]
	v_pk_add_f32 v[98:99], v[98:99], v[196:197]
	v_pk_add_f32 v[100:101], v[100:101], v[198:199]
	v_cvt_pk_bf16_f32 v184, v110, v111
	v_cvt_pk_bf16_f32 v185, v112, v113
	v_cvt_pk_bf16_f32 v186, v106, v107
	v_cvt_pk_bf16_f32 v187, v108, v109
	v_cvt_pk_bf16_f32 v188, v102, v103
	v_cvt_pk_bf16_f32 v189, v104, v105
	v_cvt_pk_bf16_f32 v190, v98, v99
	v_cvt_pk_bf16_f32 v191, v100, v101
	ds_bpermute_b32 v184, v232, v184
	ds_bpermute_b32 v185, v232, v185
	ds_bpermute_b32 v186, v232, v186
	ds_bpermute_b32 v187, v232, v187
	ds_bpermute_b32 v188, v232, v188
	ds_bpermute_b32 v189, v232, v189
	ds_bpermute_b32 v190, v232, v190
	ds_bpermute_b32 v191, v232, v191
	v_mul_f32_e32 v163, v110, v110
	v_mul_f32_e32 v200, v111, v111
	v_fmac_f32_e32 v163, v112, v112
	v_fmac_f32_e32 v200, v113, v113
	v_fmac_f32_e32 v163, v106, v106
	v_fmac_f32_e32 v200, v107, v107
	v_fmac_f32_e32 v163, v108, v108
	v_fmac_f32_e32 v200, v109, v109
	v_fmac_f32_e32 v163, v102, v102
	v_fmac_f32_e32 v200, v103, v103
	v_fmac_f32_e32 v163, v104, v104
	v_fmac_f32_e32 v200, v105, v105
	v_fmac_f32_e32 v163, v98, v98
	v_fmac_f32_e32 v200, v99, v99
	v_fmac_f32_e32 v163, v100, v100
	v_fmac_f32_e32 v200, v101, v101
	global_store_dwordx4 v150, v[110:113], s[50:51]
	global_store_dwordx4 v150, v[106:109], s[50:51] offset:16
	global_store_dwordx4 v150, v[102:105], s[50:51] offset:512
	global_store_dwordx4 v150, v[98:101], s[50:51] offset:528
	s_waitcnt lgkmcnt(0)
; __device__ __forceinline__ unsigned cvtpk(float lo, float hi) { f32x2 v = {lo, hi}; bf16x2_t b = __builtin_convertvector(v, bf16x2_t); return __builtin_bit_cast(unsigned, b); }
;     __device__ __forceinline__ void operator()(const f32x4 (&acc)[2][2][4][2], const pg8::Unit& u, int wr, int wc, int fr, int fq) const {
;     ...
;                     for (int bj = 0; bj < 2; ++bj) {
;                         const int col0 = u.pn * 256 + bj * 128 + wc * 32 + 8 * fq;
;                         const f32x4 h0 = *(const f32x4*)(src + col0) + acc[ai][bj][m][0];
;                         const f32x4 h1 = *(const f32x4*)(src + col0 + 4) + acc[ai][bj][m][1];
;                         *(f32x4*)(dst + col0) = h0; *(f32x4*)(dst + col0 + 4) = h1;
;                         if (P) { u32x4 w; w.x = cvtpk(h0[0], h0[1]); w.y = cvtpk(h0[2], h0[3]); w.z = cvtpk(h1[0], h1[1]); w.w = cvtpk(h1[2], h1[3]);
;                             *(u32x4*)(P + (size_t)grow * DM + col0) = w; }
;                         ss += (h0[0] * h0[0] + h0[1] * h0[1]) + (h0[2] * h0[2] + h0[3] * h0[3]) + (h1[0] * h1[0] + h1[1] * h1[1]) + (h1[2] * h1[2] + h1[3] * h1[3]);
;                     }
	global_store_dwordx4 v234, v[184:187], s[6:7]
	global_store_dwordx4 v234, v[188:191], s[6:7] offset:256
	v_add_f32_e32 v98, v163, v200
	s_add_u32 s50, s50, 0x10000
	s_addc_u32 s51, s51, 0
	s_add_u32 s6, s6, 0x8000
	s_addc_u32 s7, s7, 0
	global_load_dwordx4 v[184:187], v150, s[48:49]
	global_load_dwordx4 v[188:191], v150, s[48:49] offset:16
	global_load_dwordx4 v[192:195], v150, s[48:49] offset:512
	global_load_dwordx4 v[196:199], v150, s[48:49] offset:528
	s_add_u32 s48, s48, 0x10000
	s_addc_u32 s49, s49, 0
	s_waitcnt vmcnt(24)
	v_pk_add_f32 v[94:95], v[94:95], v[216:217]
	v_pk_add_f32 v[96:97], v[96:97], v[218:219]
	v_pk_add_f32 v[90:91], v[90:91], v[220:221]
	v_pk_add_f32 v[92:93], v[92:93], v[222:223]
	v_pk_add_f32 v[86:87], v[86:87], v[224:225]
	v_pk_add_f32 v[88:89], v[88:89], v[226:227]
	v_pk_add_f32 v[82:83], v[82:83], v[228:229]
	v_pk_add_f32 v[84:85], v[84:85], v[230:231]
	v_cvt_pk_bf16_f32 v216, v94, v95
	v_cvt_pk_bf16_f32 v217, v96, v97
	v_cvt_pk_bf16_f32 v218, v90, v91
	v_cvt_pk_bf16_f32 v219, v92, v93
	v_cvt_pk_bf16_f32 v220, v86, v87
	v_cvt_pk_bf16_f32 v221, v88, v89
	v_cvt_pk_bf16_f32 v222, v82, v83
	v_cvt_pk_bf16_f32 v223, v84, v85
	ds_bpermute_b32 v216, v232, v216
	ds_bpermute_b32 v217, v232, v217
	ds_bpermute_b32 v218, v232, v218
	ds_bpermute_b32 v219, v232, v219
	ds_bpermute_b32 v220, v232, v220
	ds_bpermute_b32 v221, v232, v221
	ds_bpermute_b32 v222, v232, v222
	ds_bpermute_b32 v223, v232, v223
	v_mul_f32_e32 v163, v94, v94
	v_mul_f32_e32 v200, v95, v95
	v_fmac_f32_e32 v163, v96, v96
	v_fmac_f32_e32 v200, v97, v97
	v_fmac_f32_e32 v163, v90, v90
	v_fmac_f32_e32 v200, v91, v91
	v_fmac_f32_e32 v163, v92, v92
	v_fmac_f32_e32 v200, v93, v93
	v_fmac_f32_e32 v163, v86, v86
	v_fmac_f32_e32 v200, v87, v87
	v_fmac_f32_e32 v163, v88, v88
	v_fmac_f32_e32 v200, v89, v89
	v_fmac_f32_e32 v163, v82, v82
	v_fmac_f32_e32 v200, v83, v83
	v_fmac_f32_e32 v163, v84, v84
	v_fmac_f32_e32 v200, v85, v85
	global_store_dwordx4 v150, v[94:97], s[50:51]
	global_store_dwordx4 v150, v[90:93], s[50:51] offset:16
	global_store_dwordx4 v150, v[86:89], s[50:51] offset:512
	global_store_dwordx4 v150, v[82:85], s[50:51] offset:528
	s_waitcnt lgkmcnt(0)
	global_store_dwordx4 v234, v[216:219], s[6:7]
	global_store_dwordx4 v234, v[220:223], s[6:7] offset:256
	v_add_f32_e32 v82, v163, v200
	s_add_u32 s50, s50, 0x10000
	s_addc_u32 s51, s51, 0
	s_add_u32 s6, s6, 0x8000
	s_addc_u32 s7, s7, 0
	global_load_dwordx4 v[216:219], v150, s[48:49]
	global_load_dwordx4 v[220:223], v150, s[48:49] offset:16
	global_load_dwordx4 v[224:227], v150, s[48:49] offset:512
	global_load_dwordx4 v[228:231], v150, s[48:49] offset:528
	s_add_u32 s48, s48, 0x10000
	s_addc_u32 s49, s49, 0
	s_waitcnt vmcnt(30)
	v_pk_add_f32 v[78:79], v[78:79], v[142:143]
	v_pk_add_f32 v[80:81], v[80:81], v[144:145]
	v_pk_add_f32 v[74:75], v[74:75], v[146:147]
	v_pk_add_f32 v[76:77], v[76:77], v[148:149]
	v_pk_add_f32 v[70:71], v[70:71], v[158:159]
	v_pk_add_f32 v[72:73], v[72:73], v[160:161]
	v_pk_add_f32 v[66:67], v[66:67], v[204:205]
	v_pk_add_f32 v[68:69], v[68:69], v[206:207]
	v_cvt_pk_bf16_f32 v142, v78, v79
	v_cvt_pk_bf16_f32 v143, v80, v81
	v_cvt_pk_bf16_f32 v144, v74, v75
	v_cvt_pk_bf16_f32 v145, v76, v77
	v_cvt_pk_bf16_f32 v146, v70, v71
	v_cvt_pk_bf16_f32 v147, v72, v73
	v_cvt_pk_bf16_f32 v148, v66, v67
	v_cvt_pk_bf16_f32 v149, v68, v69
	ds_bpermute_b32 v142, v232, v142
	ds_bpermute_b32 v143, v232, v143
	ds_bpermute_b32 v144, v232, v144
	ds_bpermute_b32 v145, v232, v145
	ds_bpermute_b32 v146, v232, v146
	ds_bpermute_b32 v147, v232, v147
	ds_bpermute_b32 v148, v232, v148
	ds_bpermute_b32 v149, v232, v149
	v_mul_f32_e32 v163, v78, v78
	v_mul_f32_e32 v200, v79, v79
	v_fmac_f32_e32 v163, v80, v80
	v_fmac_f32_e32 v200, v81, v81
	v_fmac_f32_e32 v163, v74, v74
	v_fmac_f32_e32 v200, v75, v75
	v_fmac_f32_e32 v163, v76, v76
	v_fmac_f32_e32 v200, v77, v77
	v_fmac_f32_e32 v163, v70, v70
	v_fmac_f32_e32 v200, v71, v71
	v_fmac_f32_e32 v163, v72, v72
	v_fmac_f32_e32 v200, v73, v73
	v_fmac_f32_e32 v163, v66, v66
	v_fmac_f32_e32 v200, v67, v67
	v_fmac_f32_e32 v163, v68, v68
	v_fmac_f32_e32 v200, v69, v69
	global_store_dwordx4 v150, v[78:81], s[50:51]
	global_store_dwordx4 v150, v[74:77], s[50:51] offset:16
	global_store_dwordx4 v150, v[70:73], s[50:51] offset:512
	global_store_dwordx4 v150, v[66:69], s[50:51] offset:528
	s_waitcnt lgkmcnt(0)
	global_store_dwordx4 v234, v[142:145], s[6:7]
	global_store_dwordx4 v234, v[146:149], s[6:7] offset:256
	v_add_f32_e32 v66, v163, v200
	s_add_u32 s50, s50, 0x50000
	s_addc_u32 s51, s51, 0
	s_add_u32 s6, s6, 0x28000
	s_addc_u32 s7, s7, 0
	global_load_dwordx4 v[142:145], v150, s[48:49]
	global_load_dwordx4 v[146:149], v150, s[48:49] offset:16
	global_load_dwordx4 v[158:161], v150, s[48:49] offset:512
	global_load_dwordx4 v[204:207], v150, s[48:49] offset:528
	s_waitcnt vmcnt(30)
; __device__ __forceinline__ unsigned cvtpk(float lo, float hi) { f32x2 v = {lo, hi}; bf16x2_t b = __builtin_convertvector(v, bf16x2_t); return __builtin_bit_cast(unsigned, b); }
;     __device__ __forceinline__ void operator()(const f32x4 (&acc)[2][2][4][2], const pg8::Unit& u, int wr, int wc, int fr, int fq) const {
;     ...
;                     for (int bj = 0; bj < 2; ++bj) {
;                         const int col0 = u.pn * 256 + bj * 128 + wc * 32 + 8 * fq;
;                         const f32x4 h0 = *(const f32x4*)(src + col0) + acc[ai][bj][m][0];
;                         const f32x4 h1 = *(const f32x4*)(src + col0 + 4) + acc[ai][bj][m][1];
;                         *(f32x4*)(dst + col0) = h0; *(f32x4*)(dst + col0 + 4) = h1;
;                         if (P) { u32x4 w; w.x = cvtpk(h0[0], h0[1]); w.y = cvtpk(h0[2], h0[3]); w.z = cvtpk(h1[0], h1[1]); w.w = cvtpk(h1[2], h1[3]);
;                             *(u32x4*)(P + (size_t)grow * DM + col0) = w; }
;                         ss += (h0[0] * h0[0] + h0[1] * h0[1]) + (h0[2] * h0[2] + h0[3] * h0[3]) + (h1[0] * h1[0] + h1[1] * h1[1]) + (h1[2] * h1[2] + h1[3] * h1[3]);
;                     }
	v_pk_add_f32 v[62:63], v[62:63], v[168:169]
	v_pk_add_f32 v[64:65], v[64:65], v[170:171]
	v_pk_add_f32 v[58:59], v[58:59], v[172:173]
	v_pk_add_f32 v[60:61], v[60:61], v[174:175]
	v_pk_add_f32 v[54:55], v[54:55], v[176:177]
	v_pk_add_f32 v[56:57], v[56:57], v[178:179]
	v_pk_add_f32 v[50:51], v[50:51], v[180:181]
	v_pk_add_f32 v[52:53], v[52:53], v[182:183]
	v_cvt_pk_bf16_f32 v168, v62, v63
	v_cvt_pk_bf16_f32 v169, v64, v65
	v_cvt_pk_bf16_f32 v170, v58, v59
	v_cvt_pk_bf16_f32 v171, v60, v61
	v_cvt_pk_bf16_f32 v172, v54, v55
	v_cvt_pk_bf16_f32 v173, v56, v57
	v_cvt_pk_bf16_f32 v174, v50, v51
	v_cvt_pk_bf16_f32 v175, v52, v53
	ds_bpermute_b32 v168, v232, v168
	ds_bpermute_b32 v169, v232, v169
	ds_bpermute_b32 v170, v232, v170
	ds_bpermute_b32 v171, v232, v171
	ds_bpermute_b32 v172, v232, v172
	ds_bpermute_b32 v173, v232, v173
	ds_bpermute_b32 v174, v232, v174
	ds_bpermute_b32 v175, v232, v175
	v_mul_f32_e32 v163, v62, v62
	v_mul_f32_e32 v200, v63, v63
	v_fmac_f32_e32 v163, v64, v64
	v_fmac_f32_e32 v200, v65, v65
	v_fmac_f32_e32 v163, v58, v58
	v_fmac_f32_e32 v200, v59, v59
	v_fmac_f32_e32 v163, v60, v60
	v_fmac_f32_e32 v200, v61, v61
	v_fmac_f32_e32 v163, v54, v54
	v_fmac_f32_e32 v200, v55, v55
	v_fmac_f32_e32 v163, v56, v56
	v_fmac_f32_e32 v200, v57, v57
	v_fmac_f32_e32 v163, v50, v50
	v_fmac_f32_e32 v200, v51, v51
	v_fmac_f32_e32 v163, v52, v52
	v_fmac_f32_e32 v200, v53, v53
	global_store_dwordx4 v150, v[62:65], s[50:51]
	global_store_dwordx4 v150, v[58:61], s[50:51] offset:16
	global_store_dwordx4 v150, v[54:57], s[50:51] offset:512
	global_store_dwordx4 v150, v[50:53], s[50:51] offset:528
	s_waitcnt lgkmcnt(0)
	global_store_dwordx4 v234, v[168:171], s[6:7]
	global_store_dwordx4 v234, v[172:175], s[6:7] offset:256
	v_add_f32_e32 v50, v163, v200
	s_add_u32 s50, s50, 0x10000
	s_addc_u32 s51, s51, 0
	s_add_u32 s6, s6, 0x8000
	s_addc_u32 s7, s7, 0
	s_waitcnt vmcnt(26)
	v_pk_add_f32 v[46:47], v[46:47], v[184:185]
	v_pk_add_f32 v[48:49], v[48:49], v[186:187]
	v_pk_add_f32 v[42:43], v[42:43], v[188:189]
	v_pk_add_f32 v[44:45], v[44:45], v[190:191]
	v_pk_add_f32 v[38:39], v[38:39], v[192:193]
	v_pk_add_f32 v[40:41], v[40:41], v[194:195]
	v_pk_add_f32 v[34:35], v[34:35], v[196:197]
	v_pk_add_f32 v[36:37], v[36:37], v[198:199]
	v_cvt_pk_bf16_f32 v184, v46, v47
	v_cvt_pk_bf16_f32 v185, v48, v49
	v_cvt_pk_bf16_f32 v186, v42, v43
	v_cvt_pk_bf16_f32 v187, v44, v45
	v_cvt_pk_bf16_f32 v188, v38, v39
	v_cvt_pk_bf16_f32 v189, v40, v41
	v_cvt_pk_bf16_f32 v190, v34, v35
	v_cvt_pk_bf16_f32 v191, v36, v37
	ds_bpermute_b32 v184, v232, v184
	ds_bpermute_b32 v185, v232, v185
	ds_bpermute_b32 v186, v232, v186
	ds_bpermute_b32 v187, v232, v187
	ds_bpermute_b32 v188, v232, v188
	ds_bpermute_b32 v189, v232, v189
	ds_bpermute_b32 v190, v232, v190
	ds_bpermute_b32 v191, v232, v191
	v_mul_f32_e32 v163, v46, v46
	v_mul_f32_e32 v200, v47, v47
	v_fmac_f32_e32 v163, v48, v48
	v_fmac_f32_e32 v200, v49, v49
	v_fmac_f32_e32 v163, v42, v42
	v_fmac_f32_e32 v200, v43, v43
	v_fmac_f32_e32 v163, v44, v44
	v_fmac_f32_e32 v200, v45, v45
	v_fmac_f32_e32 v163, v38, v38
	v_fmac_f32_e32 v200, v39, v39
	v_fmac_f32_e32 v163, v40, v40
	v_fmac_f32_e32 v200, v41, v41
	v_fmac_f32_e32 v163, v34, v34
	v_fmac_f32_e32 v200, v35, v35
	v_fmac_f32_e32 v163, v36, v36
	v_fmac_f32_e32 v200, v37, v37
	global_store_dwordx4 v150, v[46:49], s[50:51]
	global_store_dwordx4 v150, v[42:45], s[50:51] offset:16
	global_store_dwordx4 v150, v[38:41], s[50:51] offset:512
	global_store_dwordx4 v150, v[34:37], s[50:51] offset:528
	s_waitcnt lgkmcnt(0)
	global_store_dwordx4 v234, v[184:187], s[6:7]
	global_store_dwordx4 v234, v[188:191], s[6:7] offset:256
	v_add_f32_e32 v34, v163, v200
	s_add_u32 s50, s50, 0x10000
	s_addc_u32 s51, s51, 0
	s_add_u32 s6, s6, 0x8000
	s_addc_u32 s7, s7, 0
	s_waitcnt vmcnt(22)
	v_pk_add_f32 v[28:29], v[28:29], v[216:217]
	v_pk_add_f32 v[30:31], v[30:31], v[218:219]
	v_pk_add_f32 v[24:25], v[24:25], v[220:221]
	v_pk_add_f32 v[26:27], v[26:27], v[222:223]
	v_pk_add_f32 v[20:21], v[20:21], v[224:225]
	v_pk_add_f32 v[22:23], v[22:23], v[226:227]
	v_pk_add_f32 v[16:17], v[16:17], v[228:229]
	v_pk_add_f32 v[18:19], v[18:19], v[230:231]
	v_cvt_pk_bf16_f32 v216, v28, v29
	v_cvt_pk_bf16_f32 v217, v30, v31
	v_cvt_pk_bf16_f32 v218, v24, v25
	v_cvt_pk_bf16_f32 v219, v26, v27
	v_cvt_pk_bf16_f32 v220, v20, v21
	v_cvt_pk_bf16_f32 v221, v22, v23
	v_cvt_pk_bf16_f32 v222, v16, v17
	v_cvt_pk_bf16_f32 v223, v18, v19
	ds_bpermute_b32 v216, v232, v216
	ds_bpermute_b32 v217, v232, v217
	ds_bpermute_b32 v218, v232, v218
	ds_bpermute_b32 v219, v232, v219
	ds_bpermute_b32 v220, v232, v220
	ds_bpermute_b32 v221, v232, v221
	ds_bpermute_b32 v222, v232, v222
	ds_bpermute_b32 v223, v232, v223
	v_mul_f32_e32 v163, v28, v28
	v_mul_f32_e32 v200, v29, v29
	v_fmac_f32_e32 v163, v30, v30
	v_fmac_f32_e32 v200, v31, v31
	v_fmac_f32_e32 v163, v24, v24
	v_fmac_f32_e32 v200, v25, v25
	v_fmac_f32_e32 v163, v26, v26
	v_fmac_f32_e32 v200, v27, v27
	v_fmac_f32_e32 v163, v20, v20
	v_fmac_f32_e32 v200, v21, v21
	v_fmac_f32_e32 v163, v22, v22
	v_fmac_f32_e32 v200, v23, v23
	v_fmac_f32_e32 v163, v16, v16
	v_fmac_f32_e32 v200, v17, v17
	v_fmac_f32_e32 v163, v18, v18
	v_fmac_f32_e32 v200, v19, v19
	global_store_dwordx4 v150, v[28:31], s[50:51]
	global_store_dwordx4 v150, v[24:27], s[50:51] offset:16
	global_store_dwordx4 v150, v[20:23], s[50:51] offset:512
	global_store_dwordx4 v150, v[16:19], s[50:51] offset:528
	s_waitcnt lgkmcnt(0)
; __device__ __forceinline__ unsigned cvtpk(float lo, float hi) { f32x2 v = {lo, hi}; bf16x2_t b = __builtin_convertvector(v, bf16x2_t); return __builtin_bit_cast(unsigned, b); }
;     __device__ __forceinline__ void operator()(const f32x4 (&acc)[2][2][4][2], const pg8::Unit& u, int wr, int wc, int fr, int fq) const {
;     ...
;                     for (int bj = 0; bj < 2; ++bj) {
;                         const int col0 = u.pn * 256 + bj * 128 + wc * 32 + 8 * fq;
;                         const f32x4 h0 = *(const f32x4*)(src + col0) + acc[ai][bj][m][0];
;                         const f32x4 h1 = *(const f32x4*)(src + col0 + 4) + acc[ai][bj][m][1];
;                         *(f32x4*)(dst + col0) = h0; *(f32x4*)(dst + col0 + 4) = h1;
;                         if (P) { u32x4 w; w.x = cvtpk(h0[0], h0[1]); w.y = cvtpk(h0[2], h0[3]); w.z = cvtpk(h1[0], h1[1]); w.w = cvtpk(h1[2], h1[3]);
;                             *(u32x4*)(P + (size_t)grow * DM + col0) = w; }
;                         ss += (h0[0] * h0[0] + h0[1] * h0[1]) + (h0[2] * h0[2] + h0[3] * h0[3]) + (h1[0] * h1[0] + h1[1] * h1[1]) + (h1[2] * h1[2] + h1[3] * h1[3]);
;                     }
;                 }
;                 ss += __shfl_xor(ss, 16); ss += __shfl_xor(ss, 32);
;                 if (ok && fq == 0 && rowss_next) atomicAdd(rowss_next + grow, (u64)(ss * SS_SCALE));
	global_store_dwordx4 v234, v[216:219], s[6:7]
	global_store_dwordx4 v234, v[220:223], s[6:7] offset:256
	v_add_f32_e32 v16, v163, v200
	s_add_u32 s50, s50, 0x10000
	s_addc_u32 s51, s51, 0
	s_add_u32 s6, s6, 0x8000
	s_addc_u32 s7, s7, 0
	s_waitcnt vmcnt(18)
	v_pk_add_f32 v[12:13], v[12:13], v[142:143]
	v_pk_add_f32 v[14:15], v[14:15], v[144:145]
	v_pk_add_f32 v[8:9], v[8:9], v[146:147]
	v_pk_add_f32 v[10:11], v[10:11], v[148:149]
	v_pk_add_f32 v[4:5], v[4:5], v[158:159]
	v_pk_add_f32 v[6:7], v[6:7], v[160:161]
	v_pk_add_f32 v[0:1], v[0:1], v[204:205]
	v_pk_add_f32 v[2:3], v[2:3], v[206:207]
	v_cvt_pk_bf16_f32 v142, v12, v13
	v_cvt_pk_bf16_f32 v143, v14, v15
	v_cvt_pk_bf16_f32 v144, v8, v9
	v_cvt_pk_bf16_f32 v145, v10, v11
	v_cvt_pk_bf16_f32 v146, v4, v5
	v_cvt_pk_bf16_f32 v147, v6, v7
	v_cvt_pk_bf16_f32 v148, v0, v1
	v_cvt_pk_bf16_f32 v149, v2, v3
	ds_bpermute_b32 v142, v232, v142
	ds_bpermute_b32 v143, v232, v143
	ds_bpermute_b32 v144, v232, v144
	ds_bpermute_b32 v145, v232, v145
	ds_bpermute_b32 v146, v232, v146
	ds_bpermute_b32 v147, v232, v147
	ds_bpermute_b32 v148, v232, v148
	ds_bpermute_b32 v149, v232, v149
	v_mul_f32_e32 v163, v12, v12
	v_mul_f32_e32 v200, v13, v13
	v_fmac_f32_e32 v163, v14, v14
	v_fmac_f32_e32 v200, v15, v15
	v_fmac_f32_e32 v163, v8, v8
	v_fmac_f32_e32 v200, v9, v9
	v_fmac_f32_e32 v163, v10, v10
	v_fmac_f32_e32 v200, v11, v11
	v_fmac_f32_e32 v163, v4, v4
	v_fmac_f32_e32 v200, v5, v5
	v_fmac_f32_e32 v163, v6, v6
	v_fmac_f32_e32 v200, v7, v7
	v_fmac_f32_e32 v163, v0, v0
	v_fmac_f32_e32 v200, v1, v1
	v_fmac_f32_e32 v163, v2, v2
	v_fmac_f32_e32 v200, v3, v3
	global_store_dwordx4 v150, v[12:15], s[50:51]
	global_store_dwordx4 v150, v[8:11], s[50:51] offset:16
	global_store_dwordx4 v150, v[4:7], s[50:51] offset:512
	global_store_dwordx4 v150, v[0:3], s[50:51] offset:528
	s_waitcnt lgkmcnt(0)
	global_store_dwordx4 v234, v[142:145], s[6:7]
	global_store_dwordx4 v234, v[146:149], s[6:7] offset:256
	v_add_f32_e32 v0, v163, v200
	v_mbcnt_lo_u32_b32 v201, -1, 0
	v_mbcnt_hi_u32_b32 v201, -1, v201
	v_xor_b32_e32 v208, 16, v201
	v_xor_b32_e32 v209, 32, v201
	v_lshlrev_b32_e32 v208, 2, v208
	v_lshlrev_b32_e32 v209, 2, v209
	ds_bpermute_b32 v115, v208, v114
	ds_bpermute_b32 v99, v208, v98
	ds_bpermute_b32 v83, v208, v82
	ds_bpermute_b32 v67, v208, v66
	ds_bpermute_b32 v51, v208, v50
	ds_bpermute_b32 v35, v208, v34
	ds_bpermute_b32 v17, v208, v16
	ds_bpermute_b32 v1, v208, v0
	s_waitcnt lgkmcnt(0)
	v_add_f32_e32 v114, v114, v115
	v_add_f32_e32 v98, v98, v99
	v_add_f32_e32 v82, v82, v83
	v_add_f32_e32 v66, v66, v67
	v_add_f32_e32 v50, v50, v51
	v_add_f32_e32 v34, v34, v35
	v_add_f32_e32 v16, v16, v17
	v_add_f32_e32 v0, v0, v1
	ds_bpermute_b32 v115, v209, v114
	ds_bpermute_b32 v99, v209, v98
	ds_bpermute_b32 v83, v209, v82
	ds_bpermute_b32 v67, v209, v66
	ds_bpermute_b32 v51, v209, v50
	ds_bpermute_b32 v35, v209, v34
	ds_bpermute_b32 v17, v209, v16
	ds_bpermute_b32 v1, v209, v0
	s_waitcnt lgkmcnt(0)
	v_add_f32_e32 v114, v114, v115
	v_add_f32_e32 v98, v98, v99
	v_add_f32_e32 v82, v82, v83
	v_add_f32_e32 v66, v66, v67
	v_add_f32_e32 v50, v50, v51
	v_add_f32_e32 v34, v34, v35
	v_add_f32_e32 v16, v16, v17
	v_add_f32_e32 v0, v0, v1
	s_and_saveexec_b64 s[48:49], s[2:3]
	v_mul_f32_e32 v114, 0x49800000, v114
	v_trunc_f32_e32 v114, v114
	v_mul_f32_e32 v115, 0x2f800000, v114
	v_floor_f32_e32 v115, v115
	v_fmac_f32_e32 v114, 0xcf800000, v115
	v_cvt_u32_f32_e32 v116, v114
	v_cvt_u32_f32_e32 v117, v115
	global_atomic_add_x2 v162, v[116:117], s[8:9]
	v_mul_f32_e32 v98, 0x49800000, v98
	v_trunc_f32_e32 v98, v98
	v_mul_f32_e32 v99, 0x2f800000, v98
	v_floor_f32_e32 v99, v99
	v_fmac_f32_e32 v98, 0xcf800000, v99
	v_cvt_u32_f32_e32 v100, v98
	v_cvt_u32_f32_e32 v101, v99
	global_atomic_add_x2 v162, v[100:101], s[8:9] offset:128
	v_mul_f32_e32 v82, 0x49800000, v82
	v_trunc_f32_e32 v82, v82
	v_mul_f32_e32 v83, 0x2f800000, v82
	v_floor_f32_e32 v83, v83
	v_fmac_f32_e32 v82, 0xcf800000, v83
	v_cvt_u32_f32_e32 v84, v82
	v_cvt_u32_f32_e32 v85, v83
	global_atomic_add_x2 v162, v[84:85], s[8:9] offset:256
	v_mul_f32_e32 v66, 0x49800000, v66
	v_trunc_f32_e32 v66, v66
	v_mul_f32_e32 v67, 0x2f800000, v66
	v_floor_f32_e32 v67, v67
	v_fmac_f32_e32 v66, 0xcf800000, v67
	v_cvt_u32_f32_e32 v68, v66
	v_cvt_u32_f32_e32 v69, v67
	global_atomic_add_x2 v162, v[68:69], s[8:9] offset:384
	v_mul_f32_e32 v50, 0x49800000, v50
	v_trunc_f32_e32 v50, v50
	v_mul_f32_e32 v51, 0x2f800000, v50
	v_floor_f32_e32 v51, v51
	v_fmac_f32_e32 v50, 0xcf800000, v51
	v_cvt_u32_f32_e32 v52, v50
	v_cvt_u32_f32_e32 v53, v51
	global_atomic_add_x2 v162, v[52:53], s[8:9] offset:1024
	v_mul_f32_e32 v34, 0x49800000, v34
	v_trunc_f32_e32 v34, v34
	v_mul_f32_e32 v35, 0x2f800000, v34
	v_floor_f32_e32 v35, v35
	v_fmac_f32_e32 v34, 0xcf800000, v35
	v_cvt_u32_f32_e32 v36, v34
	v_cvt_u32_f32_e32 v37, v35
	global_atomic_add_x2 v162, v[36:37], s[8:9] offset:1152
	v_mul_f32_e32 v16, 0x49800000, v16
	v_trunc_f32_e32 v16, v16
	v_mul_f32_e32 v17, 0x2f800000, v16
	v_floor_f32_e32 v17, v17
	v_fmac_f32_e32 v16, 0xcf800000, v17
	v_cvt_u32_f32_e32 v18, v16
	v_cvt_u32_f32_e32 v19, v17
	global_atomic_add_x2 v162, v[18:19], s[8:9] offset:1280
	v_mul_f32_e32 v0, 0x49800000, v0
	v_trunc_f32_e32 v0, v0
	v_mul_f32_e32 v1, 0x2f800000, v0
	v_floor_f32_e32 v1, v1
	v_fmac_f32_e32 v0, 0xcf800000, v1
	v_cvt_u32_f32_e32 v2, v0
	v_cvt_u32_f32_e32 v3, v1
	global_atomic_add_x2 v162, v[2:3], s[8:9] offset:1408
	s_mov_b64 exec, s[48:49]
	s_branch .Lepi_done_dn
